# in-proj epilogue: V^T cache stores widened (16 x 2-byte stores -> 4 x dwordx2 via quad DPP transpose + v_perm), same RNE
# speedup vs baseline: 1.0027x; 1.0027x over previous
.LBB0_1316:
	v_lshlrev_b32_e32 v136, 1, v142
	v_mov_b32_e32 v137, v1
	v_lshl_add_u64 v[136:137], v[138:139], 0, v[136:137]
	v_and_b32_e32 v135, 3, v166
	v_add_u32_e32 v138, v148, v135
	v_mov_b32_e32 v139, 0x7060302
	v_bfe_u32 v176, v126, 16, 1
	v_bfe_u32 v177, v127, 16, 1
	v_bfe_u32 v178, v128, 16, 1
	v_bfe_u32 v179, v129, 16, 1
	v_add3_u32 v176, v126, v176, s31
	v_add3_u32 v177, v127, v177, s31
	v_add3_u32 v178, v128, v178, s31
	v_add3_u32 v179, v129, v179, s31
	s_mov_b32 vcc_lo, 0x55555555
	s_mov_b32 vcc_hi, 0x55555555
	v_cndmask_b32_dpp v250, v177, v176, vcc quad_perm:[1,0,3,2] row_mask:0xf bank_mask:0xf
	v_cndmask_b32_dpp v251, v179, v178, vcc quad_perm:[1,0,3,2] row_mask:0xf bank_mask:0xf
	s_not_b64 vcc, vcc
	v_cndmask_b32_dpp v176, v176, v177, vcc quad_perm:[1,0,3,2] row_mask:0xf bank_mask:0xf
	v_cndmask_b32_dpp v178, v178, v179, vcc quad_perm:[1,0,3,2] row_mask:0xf bank_mask:0xf
	s_nop 1
	v_perm_b32 v176, v176, v250, v139
	v_perm_b32 v178, v178, v251, v139
	s_mov_b32 vcc_lo, 0x33333333
	s_mov_b32 vcc_hi, 0x33333333
	v_cndmask_b32_dpp v194, v178, v176, vcc quad_perm:[2,3,0,1] row_mask:0xf bank_mask:0xf
	s_not_b64 vcc, vcc
	v_cndmask_b32_dpp v195, v176, v178, vcc quad_perm:[2,3,0,1] row_mask:0xf bank_mask:0xf
	v_mov_b32_e32 v176, v138
	v_mul_u32_u24_e32 v176, s8, v176
	v_sub_u32_e32 v176, v176, v135
	v_lshlrev_b32_e32 v176, 1, v176
	v_mov_b32_e32 v177, 0
	v_lshl_add_u64 v[250:251], v[136:137], 0, v[176:177]
	global_store_dwordx2 v[250:251], v[194:195], off
	v_bfe_u32 v176, v122, 16, 1
	v_bfe_u32 v177, v123, 16, 1
	v_bfe_u32 v178, v124, 16, 1
	v_bfe_u32 v179, v125, 16, 1
	v_add3_u32 v176, v122, v176, s31
	v_add3_u32 v177, v123, v177, s31
	v_add3_u32 v178, v124, v178, s31
	v_add3_u32 v179, v125, v179, s31
	s_mov_b32 vcc_lo, 0x55555555
	s_mov_b32 vcc_hi, 0x55555555
	v_cndmask_b32_dpp v250, v177, v176, vcc quad_perm:[1,0,3,2] row_mask:0xf bank_mask:0xf
	v_cndmask_b32_dpp v251, v179, v178, vcc quad_perm:[1,0,3,2] row_mask:0xf bank_mask:0xf
	s_not_b64 vcc, vcc
	v_cndmask_b32_dpp v176, v176, v177, vcc quad_perm:[1,0,3,2] row_mask:0xf bank_mask:0xf
	v_cndmask_b32_dpp v178, v178, v179, vcc quad_perm:[1,0,3,2] row_mask:0xf bank_mask:0xf
	s_nop 1
	v_perm_b32 v176, v176, v250, v139
	v_perm_b32 v178, v178, v251, v139
	s_mov_b32 vcc_lo, 0x33333333
	s_mov_b32 vcc_hi, 0x33333333
	v_cndmask_b32_dpp v194, v178, v176, vcc quad_perm:[2,3,0,1] row_mask:0xf bank_mask:0xf
	s_not_b64 vcc, vcc
	v_cndmask_b32_dpp v195, v176, v178, vcc quad_perm:[2,3,0,1] row_mask:0xf bank_mask:0xf
	v_or_b32_e32 v176, 16, v138
	v_mul_u32_u24_e32 v176, s8, v176
	v_sub_u32_e32 v176, v176, v135
	v_lshlrev_b32_e32 v176, 1, v176
	v_mov_b32_e32 v177, 0
	v_lshl_add_u64 v[250:251], v[136:137], 0, v[176:177]
	global_store_dwordx2 v[250:251], v[194:195], off
	v_bfe_u32 v176, v118, 16, 1
	v_bfe_u32 v177, v119, 16, 1
	v_bfe_u32 v178, v120, 16, 1
	v_bfe_u32 v179, v121, 16, 1
	v_add3_u32 v176, v118, v176, s31
	v_add3_u32 v177, v119, v177, s31
	v_add3_u32 v178, v120, v178, s31
	v_add3_u32 v179, v121, v179, s31
	s_mov_b32 vcc_lo, 0x55555555
	s_mov_b32 vcc_hi, 0x55555555
	v_cndmask_b32_dpp v250, v177, v176, vcc quad_perm:[1,0,3,2] row_mask:0xf bank_mask:0xf
	v_cndmask_b32_dpp v251, v179, v178, vcc quad_perm:[1,0,3,2] row_mask:0xf bank_mask:0xf
	s_not_b64 vcc, vcc
	v_cndmask_b32_dpp v176, v176, v177, vcc quad_perm:[1,0,3,2] row_mask:0xf bank_mask:0xf
	v_cndmask_b32_dpp v178, v178, v179, vcc quad_perm:[1,0,3,2] row_mask:0xf bank_mask:0xf
	s_nop 1
	v_perm_b32 v176, v176, v250, v139
	v_perm_b32 v178, v178, v251, v139
	s_mov_b32 vcc_lo, 0x33333333
	s_mov_b32 vcc_hi, 0x33333333
	v_cndmask_b32_dpp v194, v178, v176, vcc quad_perm:[2,3,0,1] row_mask:0xf bank_mask:0xf
	s_not_b64 vcc, vcc
	v_cndmask_b32_dpp v195, v176, v178, vcc quad_perm:[2,3,0,1] row_mask:0xf bank_mask:0xf
	v_or_b32_e32 v176, 32, v138
	v_mul_u32_u24_e32 v176, s8, v176
	v_sub_u32_e32 v176, v176, v135
	v_lshlrev_b32_e32 v176, 1, v176
	v_mov_b32_e32 v177, 0
	v_lshl_add_u64 v[250:251], v[136:137], 0, v[176:177]
	global_store_dwordx2 v[250:251], v[194:195], off
	v_bfe_u32 v176, v114, 16, 1
	v_bfe_u32 v177, v115, 16, 1
	v_bfe_u32 v178, v116, 16, 1
	v_bfe_u32 v179, v117, 16, 1
	v_add3_u32 v176, v114, v176, s31
	v_add3_u32 v177, v115, v177, s31
	v_add3_u32 v178, v116, v178, s31
	v_add3_u32 v179, v117, v179, s31
	s_mov_b32 vcc_lo, 0x55555555
	s_mov_b32 vcc_hi, 0x55555555
	v_cndmask_b32_dpp v250, v177, v176, vcc quad_perm:[1,0,3,2] row_mask:0xf bank_mask:0xf
	v_cndmask_b32_dpp v251, v179, v178, vcc quad_perm:[1,0,3,2] row_mask:0xf bank_mask:0xf
	s_not_b64 vcc, vcc
	v_cndmask_b32_dpp v176, v176, v177, vcc quad_perm:[1,0,3,2] row_mask:0xf bank_mask:0xf
	v_cndmask_b32_dpp v178, v178, v179, vcc quad_perm:[1,0,3,2] row_mask:0xf bank_mask:0xf
	s_nop 1
	v_perm_b32 v176, v176, v250, v139
	v_perm_b32 v178, v178, v251, v139
	s_mov_b32 vcc_lo, 0x33333333
	s_mov_b32 vcc_hi, 0x33333333
	v_cndmask_b32_dpp v194, v178, v176, vcc quad_perm:[2,3,0,1] row_mask:0xf bank_mask:0xf
	s_not_b64 vcc, vcc
	v_cndmask_b32_dpp v195, v176, v178, vcc quad_perm:[2,3,0,1] row_mask:0xf bank_mask:0xf
	v_or_b32_e32 v176, 48, v138
	v_mul_u32_u24_e32 v176, s8, v176
	v_sub_u32_e32 v176, v176, v135
	v_lshlrev_b32_e32 v176, 1, v176
	v_mov_b32_e32 v177, 0
	v_lshl_add_u64 v[250:251], v[136:137], 0, v[176:177]
	global_store_dwordx2 v[250:251], v[194:195], off
	s_mov_b64 s[8:9], 0

.LBB0_1336:
	v_lshlrev_b32_e32 v136, 1, v142
	v_mov_b32_e32 v137, v1
	v_lshl_add_u64 v[136:137], v[138:139], 0, v[136:137]
	v_and_b32_e32 v135, 3, v166
	v_add_u32_e32 v138, v148, v135
	v_mov_b32_e32 v139, 0x7060302
	v_bfe_u32 v176, v126, 16, 1
	v_bfe_u32 v177, v127, 16, 1
	v_bfe_u32 v178, v128, 16, 1
	v_bfe_u32 v179, v129, 16, 1
	v_add3_u32 v176, v126, v176, s31
	v_add3_u32 v177, v127, v177, s31
	v_add3_u32 v178, v128, v178, s31
	v_add3_u32 v179, v129, v179, s31
	s_mov_b32 vcc_lo, 0x55555555
	s_mov_b32 vcc_hi, 0x55555555
	v_cndmask_b32_dpp v250, v177, v176, vcc quad_perm:[1,0,3,2] row_mask:0xf bank_mask:0xf
	v_cndmask_b32_dpp v251, v179, v178, vcc quad_perm:[1,0,3,2] row_mask:0xf bank_mask:0xf
	s_not_b64 vcc, vcc
	v_cndmask_b32_dpp v176, v176, v177, vcc quad_perm:[1,0,3,2] row_mask:0xf bank_mask:0xf
	v_cndmask_b32_dpp v178, v178, v179, vcc quad_perm:[1,0,3,2] row_mask:0xf bank_mask:0xf
	s_nop 1
	v_perm_b32 v176, v176, v250, v139
	v_perm_b32 v178, v178, v251, v139
	s_mov_b32 vcc_lo, 0x33333333
	s_mov_b32 vcc_hi, 0x33333333
	v_cndmask_b32_dpp v194, v178, v176, vcc quad_perm:[2,3,0,1] row_mask:0xf bank_mask:0xf
	s_not_b64 vcc, vcc
	v_cndmask_b32_dpp v195, v176, v178, vcc quad_perm:[2,3,0,1] row_mask:0xf bank_mask:0xf
	v_mov_b32_e32 v176, v138
	v_mul_u32_u24_e32 v176, s8, v176
	v_sub_u32_e32 v176, v176, v135
	v_lshlrev_b32_e32 v176, 1, v176
	v_mov_b32_e32 v177, 0
	v_lshl_add_u64 v[250:251], v[136:137], 0, v[176:177]
	global_store_dwordx2 v[250:251], v[194:195], off
	v_bfe_u32 v176, v122, 16, 1
	v_bfe_u32 v177, v123, 16, 1
	v_bfe_u32 v178, v124, 16, 1
	v_bfe_u32 v179, v125, 16, 1
	v_add3_u32 v176, v122, v176, s31
	v_add3_u32 v177, v123, v177, s31
	v_add3_u32 v178, v124, v178, s31
	v_add3_u32 v179, v125, v179, s31
	s_mov_b32 vcc_lo, 0x55555555
	s_mov_b32 vcc_hi, 0x55555555
	v_cndmask_b32_dpp v250, v177, v176, vcc quad_perm:[1,0,3,2] row_mask:0xf bank_mask:0xf
	v_cndmask_b32_dpp v251, v179, v178, vcc quad_perm:[1,0,3,2] row_mask:0xf bank_mask:0xf
	s_not_b64 vcc, vcc
	v_cndmask_b32_dpp v176, v176, v177, vcc quad_perm:[1,0,3,2] row_mask:0xf bank_mask:0xf
	v_cndmask_b32_dpp v178, v178, v179, vcc quad_perm:[1,0,3,2] row_mask:0xf bank_mask:0xf
	s_nop 1
	v_perm_b32 v176, v176, v250, v139
	v_perm_b32 v178, v178, v251, v139
	s_mov_b32 vcc_lo, 0x33333333
	s_mov_b32 vcc_hi, 0x33333333
	v_cndmask_b32_dpp v194, v178, v176, vcc quad_perm:[2,3,0,1] row_mask:0xf bank_mask:0xf
	s_not_b64 vcc, vcc
	v_cndmask_b32_dpp v195, v176, v178, vcc quad_perm:[2,3,0,1] row_mask:0xf bank_mask:0xf
	v_or_b32_e32 v176, 16, v138
	v_mul_u32_u24_e32 v176, s8, v176
	v_sub_u32_e32 v176, v176, v135
	v_lshlrev_b32_e32 v176, 1, v176
	v_mov_b32_e32 v177, 0
	v_lshl_add_u64 v[250:251], v[136:137], 0, v[176:177]
	global_store_dwordx2 v[250:251], v[194:195], off
	v_bfe_u32 v176, v118, 16, 1
	v_bfe_u32 v177, v119, 16, 1
	v_bfe_u32 v178, v120, 16, 1
	v_bfe_u32 v179, v121, 16, 1
	v_add3_u32 v176, v118, v176, s31
	v_add3_u32 v177, v119, v177, s31
	v_add3_u32 v178, v120, v178, s31
	v_add3_u32 v179, v121, v179, s31
	s_mov_b32 vcc_lo, 0x55555555
	s_mov_b32 vcc_hi, 0x55555555
	v_cndmask_b32_dpp v250, v177, v176, vcc quad_perm:[1,0,3,2] row_mask:0xf bank_mask:0xf
	v_cndmask_b32_dpp v251, v179, v178, vcc quad_perm:[1,0,3,2] row_mask:0xf bank_mask:0xf
	s_not_b64 vcc, vcc
	v_cndmask_b32_dpp v176, v176, v177, vcc quad_perm:[1,0,3,2] row_mask:0xf bank_mask:0xf
	v_cndmask_b32_dpp v178, v178, v179, vcc quad_perm:[1,0,3,2] row_mask:0xf bank_mask:0xf
	s_nop 1
	v_perm_b32 v176, v176, v250, v139
	v_perm_b32 v178, v178, v251, v139
	s_mov_b32 vcc_lo, 0x33333333
	s_mov_b32 vcc_hi, 0x33333333
	v_cndmask_b32_dpp v194, v178, v176, vcc quad_perm:[2,3,0,1] row_mask:0xf bank_mask:0xf
	s_not_b64 vcc, vcc
	v_cndmask_b32_dpp v195, v176, v178, vcc quad_perm:[2,3,0,1] row_mask:0xf bank_mask:0xf
	v_or_b32_e32 v176, 32, v138
	v_mul_u32_u24_e32 v176, s8, v176
	v_sub_u32_e32 v176, v176, v135
	v_lshlrev_b32_e32 v176, 1, v176
	v_mov_b32_e32 v177, 0
	v_lshl_add_u64 v[250:251], v[136:137], 0, v[176:177]
	global_store_dwordx2 v[250:251], v[194:195], off
	v_bfe_u32 v176, v114, 16, 1
	v_bfe_u32 v177, v115, 16, 1
	v_bfe_u32 v178, v116, 16, 1
	v_bfe_u32 v179, v117, 16, 1
	v_add3_u32 v176, v114, v176, s31
	v_add3_u32 v177, v115, v177, s31
	v_add3_u32 v178, v116, v178, s31
	v_add3_u32 v179, v117, v179, s31
	s_mov_b32 vcc_lo, 0x55555555
	s_mov_b32 vcc_hi, 0x55555555
	v_cndmask_b32_dpp v250, v177, v176, vcc quad_perm:[1,0,3,2] row_mask:0xf bank_mask:0xf
	v_cndmask_b32_dpp v251, v179, v178, vcc quad_perm:[1,0,3,2] row_mask:0xf bank_mask:0xf
	s_not_b64 vcc, vcc
	v_cndmask_b32_dpp v176, v176, v177, vcc quad_perm:[1,0,3,2] row_mask:0xf bank_mask:0xf
	v_cndmask_b32_dpp v178, v178, v179, vcc quad_perm:[1,0,3,2] row_mask:0xf bank_mask:0xf
	s_nop 1
	v_perm_b32 v176, v176, v250, v139
	v_perm_b32 v178, v178, v251, v139
	s_mov_b32 vcc_lo, 0x33333333
	s_mov_b32 vcc_hi, 0x33333333
	v_cndmask_b32_dpp v194, v178, v176, vcc quad_perm:[2,3,0,1] row_mask:0xf bank_mask:0xf
	s_not_b64 vcc, vcc
	v_cndmask_b32_dpp v195, v176, v178, vcc quad_perm:[2,3,0,1] row_mask:0xf bank_mask:0xf
	v_or_b32_e32 v176, 48, v138
	v_mul_u32_u24_e32 v176, s8, v176
	v_sub_u32_e32 v176, v176, v135
	v_lshlrev_b32_e32 v176, 1, v176
	v_mov_b32_e32 v177, 0
	v_lshl_add_u64 v[250:251], v[136:137], 0, v[176:177]
	global_store_dwordx2 v[250:251], v[194:195], off

.LBB0_1362:
	v_lshlrev_b32_e32 v118, 1, v114
	v_mov_b32_e32 v119, v1
	v_lshl_add_u64 v[118:119], v[120:121], 0, v[118:119]
	v_and_b32_e32 v115, 3, v166
	v_add_u32_e32 v117, v148, v115
	v_mov_b32_e32 v120, 0x7060302
	v_bfe_u32 v176, v110, 16, 1
	v_bfe_u32 v177, v111, 16, 1
	v_bfe_u32 v178, v112, 16, 1
	v_bfe_u32 v179, v113, 16, 1
	v_add3_u32 v176, v110, v176, s31
	v_add3_u32 v177, v111, v177, s31
	v_add3_u32 v178, v112, v178, s31
	v_add3_u32 v179, v113, v179, s31
	s_mov_b32 vcc_lo, 0x55555555
	s_mov_b32 vcc_hi, 0x55555555
	v_cndmask_b32_dpp v250, v177, v176, vcc quad_perm:[1,0,3,2] row_mask:0xf bank_mask:0xf
	v_cndmask_b32_dpp v251, v179, v178, vcc quad_perm:[1,0,3,2] row_mask:0xf bank_mask:0xf
	s_not_b64 vcc, vcc
	v_cndmask_b32_dpp v176, v176, v177, vcc quad_perm:[1,0,3,2] row_mask:0xf bank_mask:0xf
	v_cndmask_b32_dpp v178, v178, v179, vcc quad_perm:[1,0,3,2] row_mask:0xf bank_mask:0xf
	s_nop 1
	v_perm_b32 v176, v176, v250, v120
	v_perm_b32 v178, v178, v251, v120
	s_mov_b32 vcc_lo, 0x33333333
	s_mov_b32 vcc_hi, 0x33333333
	v_cndmask_b32_dpp v194, v178, v176, vcc quad_perm:[2,3,0,1] row_mask:0xf bank_mask:0xf
	s_not_b64 vcc, vcc
	v_cndmask_b32_dpp v195, v176, v178, vcc quad_perm:[2,3,0,1] row_mask:0xf bank_mask:0xf
	v_mov_b32_e32 v176, v117
	v_mul_u32_u24_e32 v176, s8, v176
	v_sub_u32_e32 v176, v176, v115
	v_lshlrev_b32_e32 v176, 1, v176
	v_mov_b32_e32 v177, 0
	v_lshl_add_u64 v[250:251], v[118:119], 0, v[176:177]
	global_store_dwordx2 v[250:251], v[194:195], off
	v_bfe_u32 v176, v106, 16, 1
	v_bfe_u32 v177, v107, 16, 1
	v_bfe_u32 v178, v108, 16, 1
	v_bfe_u32 v179, v109, 16, 1
	v_add3_u32 v176, v106, v176, s31
	v_add3_u32 v177, v107, v177, s31
	v_add3_u32 v178, v108, v178, s31
	v_add3_u32 v179, v109, v179, s31
	s_mov_b32 vcc_lo, 0x55555555
	s_mov_b32 vcc_hi, 0x55555555
	v_cndmask_b32_dpp v250, v177, v176, vcc quad_perm:[1,0,3,2] row_mask:0xf bank_mask:0xf
	v_cndmask_b32_dpp v251, v179, v178, vcc quad_perm:[1,0,3,2] row_mask:0xf bank_mask:0xf
	s_not_b64 vcc, vcc
	v_cndmask_b32_dpp v176, v176, v177, vcc quad_perm:[1,0,3,2] row_mask:0xf bank_mask:0xf
	v_cndmask_b32_dpp v178, v178, v179, vcc quad_perm:[1,0,3,2] row_mask:0xf bank_mask:0xf
	s_nop 1
	v_perm_b32 v176, v176, v250, v120
	v_perm_b32 v178, v178, v251, v120
	s_mov_b32 vcc_lo, 0x33333333
	s_mov_b32 vcc_hi, 0x33333333
	v_cndmask_b32_dpp v194, v178, v176, vcc quad_perm:[2,3,0,1] row_mask:0xf bank_mask:0xf
	s_not_b64 vcc, vcc
	v_cndmask_b32_dpp v195, v176, v178, vcc quad_perm:[2,3,0,1] row_mask:0xf bank_mask:0xf
	v_or_b32_e32 v176, 16, v117
	v_mul_u32_u24_e32 v176, s8, v176
	v_sub_u32_e32 v176, v176, v115
	v_lshlrev_b32_e32 v176, 1, v176
	v_mov_b32_e32 v177, 0
	v_lshl_add_u64 v[250:251], v[118:119], 0, v[176:177]
	global_store_dwordx2 v[250:251], v[194:195], off
	v_bfe_u32 v176, v102, 16, 1
	v_bfe_u32 v177, v103, 16, 1
	v_bfe_u32 v178, v104, 16, 1
	v_bfe_u32 v179, v105, 16, 1
	v_add3_u32 v176, v102, v176, s31
	v_add3_u32 v177, v103, v177, s31
	v_add3_u32 v178, v104, v178, s31
	v_add3_u32 v179, v105, v179, s31
	s_mov_b32 vcc_lo, 0x55555555
	s_mov_b32 vcc_hi, 0x55555555
	v_cndmask_b32_dpp v250, v177, v176, vcc quad_perm:[1,0,3,2] row_mask:0xf bank_mask:0xf
	v_cndmask_b32_dpp v251, v179, v178, vcc quad_perm:[1,0,3,2] row_mask:0xf bank_mask:0xf
	s_not_b64 vcc, vcc
	v_cndmask_b32_dpp v176, v176, v177, vcc quad_perm:[1,0,3,2] row_mask:0xf bank_mask:0xf
	v_cndmask_b32_dpp v178, v178, v179, vcc quad_perm:[1,0,3,2] row_mask:0xf bank_mask:0xf
	s_nop 1
	v_perm_b32 v176, v176, v250, v120
	v_perm_b32 v178, v178, v251, v120
	s_mov_b32 vcc_lo, 0x33333333
	s_mov_b32 vcc_hi, 0x33333333
	v_cndmask_b32_dpp v194, v178, v176, vcc quad_perm:[2,3,0,1] row_mask:0xf bank_mask:0xf
	s_not_b64 vcc, vcc
	v_cndmask_b32_dpp v195, v176, v178, vcc quad_perm:[2,3,0,1] row_mask:0xf bank_mask:0xf
	v_or_b32_e32 v176, 32, v117
	v_mul_u32_u24_e32 v176, s8, v176
	v_sub_u32_e32 v176, v176, v115
	v_lshlrev_b32_e32 v176, 1, v176
	v_mov_b32_e32 v177, 0
	v_lshl_add_u64 v[250:251], v[118:119], 0, v[176:177]
	global_store_dwordx2 v[250:251], v[194:195], off
	v_bfe_u32 v176, v98, 16, 1
	v_bfe_u32 v177, v99, 16, 1
	v_bfe_u32 v178, v100, 16, 1
	v_bfe_u32 v179, v101, 16, 1
	v_add3_u32 v176, v98, v176, s31
	v_add3_u32 v177, v99, v177, s31
	v_add3_u32 v178, v100, v178, s31
	v_add3_u32 v179, v101, v179, s31
	s_mov_b32 vcc_lo, 0x55555555
	s_mov_b32 vcc_hi, 0x55555555
	v_cndmask_b32_dpp v250, v177, v176, vcc quad_perm:[1,0,3,2] row_mask:0xf bank_mask:0xf
	v_cndmask_b32_dpp v251, v179, v178, vcc quad_perm:[1,0,3,2] row_mask:0xf bank_mask:0xf
	s_not_b64 vcc, vcc
	v_cndmask_b32_dpp v176, v176, v177, vcc quad_perm:[1,0,3,2] row_mask:0xf bank_mask:0xf
	v_cndmask_b32_dpp v178, v178, v179, vcc quad_perm:[1,0,3,2] row_mask:0xf bank_mask:0xf
	s_nop 1
	v_perm_b32 v176, v176, v250, v120
	v_perm_b32 v178, v178, v251, v120
	s_mov_b32 vcc_lo, 0x33333333
	s_mov_b32 vcc_hi, 0x33333333
	v_cndmask_b32_dpp v194, v178, v176, vcc quad_perm:[2,3,0,1] row_mask:0xf bank_mask:0xf
	s_not_b64 vcc, vcc
	v_cndmask_b32_dpp v195, v176, v178, vcc quad_perm:[2,3,0,1] row_mask:0xf bank_mask:0xf
	v_or_b32_e32 v176, 48, v117
	v_mul_u32_u24_e32 v176, s8, v176
	v_sub_u32_e32 v176, v176, v115
	v_lshlrev_b32_e32 v176, 1, v176
	v_mov_b32_e32 v177, 0
	v_lshl_add_u64 v[250:251], v[118:119], 0, v[176:177]
	global_store_dwordx2 v[250:251], v[194:195], off
	s_mov_b64 s[0:1], 0

.LBB0_1383:
	v_lshlrev_b32_e32 v114, 1, v114
	v_mov_b32_e32 v115, v1
	v_lshl_add_u64 v[114:115], v[118:119], 0, v[114:115]
	v_and_b32_e32 v116, 3, v166
	v_add_u32_e32 v117, v148, v116
	v_mov_b32_e32 v118, 0x7060302
	v_bfe_u32 v176, v110, 16, 1
	v_bfe_u32 v177, v111, 16, 1
	v_bfe_u32 v178, v112, 16, 1
	v_bfe_u32 v179, v113, 16, 1
	v_add3_u32 v176, v110, v176, s31
	v_add3_u32 v177, v111, v177, s31
	v_add3_u32 v178, v112, v178, s31
	v_add3_u32 v179, v113, v179, s31
	s_mov_b32 vcc_lo, 0x55555555
	s_mov_b32 vcc_hi, 0x55555555
	v_cndmask_b32_dpp v250, v177, v176, vcc quad_perm:[1,0,3,2] row_mask:0xf bank_mask:0xf
	v_cndmask_b32_dpp v251, v179, v178, vcc quad_perm:[1,0,3,2] row_mask:0xf bank_mask:0xf
	s_not_b64 vcc, vcc
	v_cndmask_b32_dpp v176, v176, v177, vcc quad_perm:[1,0,3,2] row_mask:0xf bank_mask:0xf
	v_cndmask_b32_dpp v178, v178, v179, vcc quad_perm:[1,0,3,2] row_mask:0xf bank_mask:0xf
	s_nop 1
	v_perm_b32 v176, v176, v250, v118
	v_perm_b32 v178, v178, v251, v118
	s_mov_b32 vcc_lo, 0x33333333
	s_mov_b32 vcc_hi, 0x33333333
	v_cndmask_b32_dpp v194, v178, v176, vcc quad_perm:[2,3,0,1] row_mask:0xf bank_mask:0xf
	s_not_b64 vcc, vcc
	v_cndmask_b32_dpp v195, v176, v178, vcc quad_perm:[2,3,0,1] row_mask:0xf bank_mask:0xf
	v_mov_b32_e32 v176, v117
	v_mul_u32_u24_e32 v176, s8, v176
	v_sub_u32_e32 v176, v176, v116
	v_lshlrev_b32_e32 v176, 1, v176
	v_mov_b32_e32 v177, 0
	v_lshl_add_u64 v[250:251], v[114:115], 0, v[176:177]
	global_store_dwordx2 v[250:251], v[194:195], off
	v_bfe_u32 v176, v106, 16, 1
	v_bfe_u32 v177, v107, 16, 1
	v_bfe_u32 v178, v108, 16, 1
	v_bfe_u32 v179, v109, 16, 1
	v_add3_u32 v176, v106, v176, s31
	v_add3_u32 v177, v107, v177, s31
	v_add3_u32 v178, v108, v178, s31
	v_add3_u32 v179, v109, v179, s31
	s_mov_b32 vcc_lo, 0x55555555
	s_mov_b32 vcc_hi, 0x55555555
	v_cndmask_b32_dpp v250, v177, v176, vcc quad_perm:[1,0,3,2] row_mask:0xf bank_mask:0xf
	v_cndmask_b32_dpp v251, v179, v178, vcc quad_perm:[1,0,3,2] row_mask:0xf bank_mask:0xf
	s_not_b64 vcc, vcc
	v_cndmask_b32_dpp v176, v176, v177, vcc quad_perm:[1,0,3,2] row_mask:0xf bank_mask:0xf
	v_cndmask_b32_dpp v178, v178, v179, vcc quad_perm:[1,0,3,2] row_mask:0xf bank_mask:0xf
	s_nop 1
	v_perm_b32 v176, v176, v250, v118
	v_perm_b32 v178, v178, v251, v118
	s_mov_b32 vcc_lo, 0x33333333
	s_mov_b32 vcc_hi, 0x33333333
	v_cndmask_b32_dpp v194, v178, v176, vcc quad_perm:[2,3,0,1] row_mask:0xf bank_mask:0xf
	s_not_b64 vcc, vcc
	v_cndmask_b32_dpp v195, v176, v178, vcc quad_perm:[2,3,0,1] row_mask:0xf bank_mask:0xf
	v_or_b32_e32 v176, 16, v117
	v_mul_u32_u24_e32 v176, s8, v176
	v_sub_u32_e32 v176, v176, v116
	v_lshlrev_b32_e32 v176, 1, v176
	v_mov_b32_e32 v177, 0
	v_lshl_add_u64 v[250:251], v[114:115], 0, v[176:177]
	global_store_dwordx2 v[250:251], v[194:195], off
	v_bfe_u32 v176, v102, 16, 1
	v_bfe_u32 v177, v103, 16, 1
	v_bfe_u32 v178, v104, 16, 1
	v_bfe_u32 v179, v105, 16, 1
	v_add3_u32 v176, v102, v176, s31
	v_add3_u32 v177, v103, v177, s31
	v_add3_u32 v178, v104, v178, s31
	v_add3_u32 v179, v105, v179, s31
	s_mov_b32 vcc_lo, 0x55555555
	s_mov_b32 vcc_hi, 0x55555555
	v_cndmask_b32_dpp v250, v177, v176, vcc quad_perm:[1,0,3,2] row_mask:0xf bank_mask:0xf
	v_cndmask_b32_dpp v251, v179, v178, vcc quad_perm:[1,0,3,2] row_mask:0xf bank_mask:0xf
	s_not_b64 vcc, vcc
	v_cndmask_b32_dpp v176, v176, v177, vcc quad_perm:[1,0,3,2] row_mask:0xf bank_mask:0xf
	v_cndmask_b32_dpp v178, v178, v179, vcc quad_perm:[1,0,3,2] row_mask:0xf bank_mask:0xf
	s_nop 1
	v_perm_b32 v176, v176, v250, v118
	v_perm_b32 v178, v178, v251, v118
	s_mov_b32 vcc_lo, 0x33333333
	s_mov_b32 vcc_hi, 0x33333333
	v_cndmask_b32_dpp v194, v178, v176, vcc quad_perm:[2,3,0,1] row_mask:0xf bank_mask:0xf
	s_not_b64 vcc, vcc
	v_cndmask_b32_dpp v195, v176, v178, vcc quad_perm:[2,3,0,1] row_mask:0xf bank_mask:0xf
	v_or_b32_e32 v176, 32, v117
	v_mul_u32_u24_e32 v176, s8, v176
	v_sub_u32_e32 v176, v176, v116
	v_lshlrev_b32_e32 v176, 1, v176
	v_mov_b32_e32 v177, 0
	v_lshl_add_u64 v[250:251], v[114:115], 0, v[176:177]
	global_store_dwordx2 v[250:251], v[194:195], off
	v_bfe_u32 v176, v98, 16, 1
	v_bfe_u32 v177, v99, 16, 1
	v_bfe_u32 v178, v100, 16, 1
	v_bfe_u32 v179, v101, 16, 1
	v_add3_u32 v176, v98, v176, s31
	v_add3_u32 v177, v99, v177, s31
	v_add3_u32 v178, v100, v178, s31
	v_add3_u32 v179, v101, v179, s31
	s_mov_b32 vcc_lo, 0x55555555
	s_mov_b32 vcc_hi, 0x55555555
	v_cndmask_b32_dpp v250, v177, v176, vcc quad_perm:[1,0,3,2] row_mask:0xf bank_mask:0xf
	v_cndmask_b32_dpp v251, v179, v178, vcc quad_perm:[1,0,3,2] row_mask:0xf bank_mask:0xf
	s_not_b64 vcc, vcc
	v_cndmask_b32_dpp v176, v176, v177, vcc quad_perm:[1,0,3,2] row_mask:0xf bank_mask:0xf
	v_cndmask_b32_dpp v178, v178, v179, vcc quad_perm:[1,0,3,2] row_mask:0xf bank_mask:0xf
	s_nop 1
	v_perm_b32 v176, v176, v250, v118
	v_perm_b32 v178, v178, v251, v118
	s_mov_b32 vcc_lo, 0x33333333
	s_mov_b32 vcc_hi, 0x33333333
	v_cndmask_b32_dpp v194, v178, v176, vcc quad_perm:[2,3,0,1] row_mask:0xf bank_mask:0xf
	s_not_b64 vcc, vcc
	v_cndmask_b32_dpp v195, v176, v178, vcc quad_perm:[2,3,0,1] row_mask:0xf bank_mask:0xf
	v_or_b32_e32 v176, 48, v117
	v_mul_u32_u24_e32 v176, s8, v176
	v_sub_u32_e32 v176, v176, v116
	v_lshlrev_b32_e32 v176, 1, v176
	v_mov_b32_e32 v177, 0
	v_lshl_add_u64 v[250:251], v[114:115], 0, v[176:177]
	global_store_dwordx2 v[250:251], v[194:195], off

.LBB0_1409:
	v_lshlrev_b32_e32 v102, 1, v98
	v_mov_b32_e32 v103, v1
	v_lshl_add_u64 v[102:103], v[104:105], 0, v[102:103]
	v_and_b32_e32 v99, 3, v166
	v_add_u32_e32 v101, v148, v99
	v_mov_b32_e32 v104, 0x7060302
	v_bfe_u32 v176, v94, 16, 1
	v_bfe_u32 v177, v95, 16, 1
	v_bfe_u32 v178, v96, 16, 1
	v_bfe_u32 v179, v97, 16, 1
	v_add3_u32 v176, v94, v176, s31
	v_add3_u32 v177, v95, v177, s31
	v_add3_u32 v178, v96, v178, s31
	v_add3_u32 v179, v97, v179, s31
	s_mov_b32 vcc_lo, 0x55555555
	s_mov_b32 vcc_hi, 0x55555555
	v_cndmask_b32_dpp v250, v177, v176, vcc quad_perm:[1,0,3,2] row_mask:0xf bank_mask:0xf
	v_cndmask_b32_dpp v251, v179, v178, vcc quad_perm:[1,0,3,2] row_mask:0xf bank_mask:0xf
	s_not_b64 vcc, vcc
	v_cndmask_b32_dpp v176, v176, v177, vcc quad_perm:[1,0,3,2] row_mask:0xf bank_mask:0xf
	v_cndmask_b32_dpp v178, v178, v179, vcc quad_perm:[1,0,3,2] row_mask:0xf bank_mask:0xf
	s_nop 1
	v_perm_b32 v176, v176, v250, v104
	v_perm_b32 v178, v178, v251, v104
	s_mov_b32 vcc_lo, 0x33333333
	s_mov_b32 vcc_hi, 0x33333333
	v_cndmask_b32_dpp v194, v178, v176, vcc quad_perm:[2,3,0,1] row_mask:0xf bank_mask:0xf
	s_not_b64 vcc, vcc
	v_cndmask_b32_dpp v195, v176, v178, vcc quad_perm:[2,3,0,1] row_mask:0xf bank_mask:0xf
	v_mov_b32_e32 v176, v101
	v_mul_u32_u24_e32 v176, s8, v176
	v_sub_u32_e32 v176, v176, v99
	v_lshlrev_b32_e32 v176, 1, v176
	v_mov_b32_e32 v177, 0
	v_lshl_add_u64 v[250:251], v[102:103], 0, v[176:177]
	global_store_dwordx2 v[250:251], v[194:195], off
	v_bfe_u32 v176, v90, 16, 1
	v_bfe_u32 v177, v91, 16, 1
	v_bfe_u32 v178, v92, 16, 1
	v_bfe_u32 v179, v93, 16, 1
	v_add3_u32 v176, v90, v176, s31
	v_add3_u32 v177, v91, v177, s31
	v_add3_u32 v178, v92, v178, s31
	v_add3_u32 v179, v93, v179, s31
	s_mov_b32 vcc_lo, 0x55555555
	s_mov_b32 vcc_hi, 0x55555555
	v_cndmask_b32_dpp v250, v177, v176, vcc quad_perm:[1,0,3,2] row_mask:0xf bank_mask:0xf
	v_cndmask_b32_dpp v251, v179, v178, vcc quad_perm:[1,0,3,2] row_mask:0xf bank_mask:0xf
	s_not_b64 vcc, vcc
	v_cndmask_b32_dpp v176, v176, v177, vcc quad_perm:[1,0,3,2] row_mask:0xf bank_mask:0xf
	v_cndmask_b32_dpp v178, v178, v179, vcc quad_perm:[1,0,3,2] row_mask:0xf bank_mask:0xf
	s_nop 1
	v_perm_b32 v176, v176, v250, v104
	v_perm_b32 v178, v178, v251, v104
	s_mov_b32 vcc_lo, 0x33333333
	s_mov_b32 vcc_hi, 0x33333333
	v_cndmask_b32_dpp v194, v178, v176, vcc quad_perm:[2,3,0,1] row_mask:0xf bank_mask:0xf
	s_not_b64 vcc, vcc
	v_cndmask_b32_dpp v195, v176, v178, vcc quad_perm:[2,3,0,1] row_mask:0xf bank_mask:0xf
	v_or_b32_e32 v176, 16, v101
	v_mul_u32_u24_e32 v176, s8, v176
	v_sub_u32_e32 v176, v176, v99
	v_lshlrev_b32_e32 v176, 1, v176
	v_mov_b32_e32 v177, 0
	v_lshl_add_u64 v[250:251], v[102:103], 0, v[176:177]
	global_store_dwordx2 v[250:251], v[194:195], off
	v_bfe_u32 v176, v86, 16, 1
	v_bfe_u32 v177, v87, 16, 1
	v_bfe_u32 v178, v88, 16, 1
	v_bfe_u32 v179, v89, 16, 1
	v_add3_u32 v176, v86, v176, s31
	v_add3_u32 v177, v87, v177, s31
	v_add3_u32 v178, v88, v178, s31
	v_add3_u32 v179, v89, v179, s31
	s_mov_b32 vcc_lo, 0x55555555
	s_mov_b32 vcc_hi, 0x55555555
	v_cndmask_b32_dpp v250, v177, v176, vcc quad_perm:[1,0,3,2] row_mask:0xf bank_mask:0xf
	v_cndmask_b32_dpp v251, v179, v178, vcc quad_perm:[1,0,3,2] row_mask:0xf bank_mask:0xf
	s_not_b64 vcc, vcc
	v_cndmask_b32_dpp v176, v176, v177, vcc quad_perm:[1,0,3,2] row_mask:0xf bank_mask:0xf
	v_cndmask_b32_dpp v178, v178, v179, vcc quad_perm:[1,0,3,2] row_mask:0xf bank_mask:0xf
	s_nop 1
	v_perm_b32 v176, v176, v250, v104
	v_perm_b32 v178, v178, v251, v104
	s_mov_b32 vcc_lo, 0x33333333
	s_mov_b32 vcc_hi, 0x33333333
	v_cndmask_b32_dpp v194, v178, v176, vcc quad_perm:[2,3,0,1] row_mask:0xf bank_mask:0xf
	s_not_b64 vcc, vcc
	v_cndmask_b32_dpp v195, v176, v178, vcc quad_perm:[2,3,0,1] row_mask:0xf bank_mask:0xf
	v_or_b32_e32 v176, 32, v101
	v_mul_u32_u24_e32 v176, s8, v176
	v_sub_u32_e32 v176, v176, v99
	v_lshlrev_b32_e32 v176, 1, v176
	v_mov_b32_e32 v177, 0
	v_lshl_add_u64 v[250:251], v[102:103], 0, v[176:177]
	global_store_dwordx2 v[250:251], v[194:195], off
	v_bfe_u32 v176, v82, 16, 1
	v_bfe_u32 v177, v83, 16, 1
	v_bfe_u32 v178, v84, 16, 1
	v_bfe_u32 v179, v85, 16, 1
	v_add3_u32 v176, v82, v176, s31
	v_add3_u32 v177, v83, v177, s31
	v_add3_u32 v178, v84, v178, s31
	v_add3_u32 v179, v85, v179, s31
	s_mov_b32 vcc_lo, 0x55555555
	s_mov_b32 vcc_hi, 0x55555555
	v_cndmask_b32_dpp v250, v177, v176, vcc quad_perm:[1,0,3,2] row_mask:0xf bank_mask:0xf
	v_cndmask_b32_dpp v251, v179, v178, vcc quad_perm:[1,0,3,2] row_mask:0xf bank_mask:0xf
	s_not_b64 vcc, vcc
	v_cndmask_b32_dpp v176, v176, v177, vcc quad_perm:[1,0,3,2] row_mask:0xf bank_mask:0xf
	v_cndmask_b32_dpp v178, v178, v179, vcc quad_perm:[1,0,3,2] row_mask:0xf bank_mask:0xf
	s_nop 1
	v_perm_b32 v176, v176, v250, v104
	v_perm_b32 v178, v178, v251, v104
	s_mov_b32 vcc_lo, 0x33333333
	s_mov_b32 vcc_hi, 0x33333333
	v_cndmask_b32_dpp v194, v178, v176, vcc quad_perm:[2,3,0,1] row_mask:0xf bank_mask:0xf
	s_not_b64 vcc, vcc
	v_cndmask_b32_dpp v195, v176, v178, vcc quad_perm:[2,3,0,1] row_mask:0xf bank_mask:0xf
	v_or_b32_e32 v176, 48, v101
	v_mul_u32_u24_e32 v176, s8, v176
	v_sub_u32_e32 v176, v176, v99
	v_lshlrev_b32_e32 v176, 1, v176
	v_mov_b32_e32 v177, 0
	v_lshl_add_u64 v[250:251], v[102:103], 0, v[176:177]
	global_store_dwordx2 v[250:251], v[194:195], off
	s_mov_b64 s[0:1], 0

.LBB0_1430:
	v_lshlrev_b32_e32 v98, 1, v98
	v_mov_b32_e32 v99, v1
	v_lshl_add_u64 v[98:99], v[102:103], 0, v[98:99]
	v_and_b32_e32 v100, 3, v166
	v_add_u32_e32 v101, v148, v100
	v_mov_b32_e32 v102, 0x7060302
	v_bfe_u32 v176, v94, 16, 1
	v_bfe_u32 v177, v95, 16, 1
	v_bfe_u32 v178, v96, 16, 1
	v_bfe_u32 v179, v97, 16, 1
	v_add3_u32 v176, v94, v176, s31
	v_add3_u32 v177, v95, v177, s31
	v_add3_u32 v178, v96, v178, s31
	v_add3_u32 v179, v97, v179, s31
	s_mov_b32 vcc_lo, 0x55555555
	s_mov_b32 vcc_hi, 0x55555555
	v_cndmask_b32_dpp v250, v177, v176, vcc quad_perm:[1,0,3,2] row_mask:0xf bank_mask:0xf
	v_cndmask_b32_dpp v251, v179, v178, vcc quad_perm:[1,0,3,2] row_mask:0xf bank_mask:0xf
	s_not_b64 vcc, vcc
	v_cndmask_b32_dpp v176, v176, v177, vcc quad_perm:[1,0,3,2] row_mask:0xf bank_mask:0xf
	v_cndmask_b32_dpp v178, v178, v179, vcc quad_perm:[1,0,3,2] row_mask:0xf bank_mask:0xf
	s_nop 1
	v_perm_b32 v176, v176, v250, v102
	v_perm_b32 v178, v178, v251, v102
	s_mov_b32 vcc_lo, 0x33333333
	s_mov_b32 vcc_hi, 0x33333333
	v_cndmask_b32_dpp v194, v178, v176, vcc quad_perm:[2,3,0,1] row_mask:0xf bank_mask:0xf
	s_not_b64 vcc, vcc
	v_cndmask_b32_dpp v195, v176, v178, vcc quad_perm:[2,3,0,1] row_mask:0xf bank_mask:0xf
	v_mov_b32_e32 v176, v101
	v_mul_u32_u24_e32 v176, s8, v176
	v_sub_u32_e32 v176, v176, v100
	v_lshlrev_b32_e32 v176, 1, v176
	v_mov_b32_e32 v177, 0
	v_lshl_add_u64 v[250:251], v[98:99], 0, v[176:177]
	global_store_dwordx2 v[250:251], v[194:195], off
	v_bfe_u32 v176, v90, 16, 1
	v_bfe_u32 v177, v91, 16, 1
	v_bfe_u32 v178, v92, 16, 1
	v_bfe_u32 v179, v93, 16, 1
	v_add3_u32 v176, v90, v176, s31
	v_add3_u32 v177, v91, v177, s31
	v_add3_u32 v178, v92, v178, s31
	v_add3_u32 v179, v93, v179, s31
	s_mov_b32 vcc_lo, 0x55555555
	s_mov_b32 vcc_hi, 0x55555555
	v_cndmask_b32_dpp v250, v177, v176, vcc quad_perm:[1,0,3,2] row_mask:0xf bank_mask:0xf
	v_cndmask_b32_dpp v251, v179, v178, vcc quad_perm:[1,0,3,2] row_mask:0xf bank_mask:0xf
	s_not_b64 vcc, vcc
	v_cndmask_b32_dpp v176, v176, v177, vcc quad_perm:[1,0,3,2] row_mask:0xf bank_mask:0xf
	v_cndmask_b32_dpp v178, v178, v179, vcc quad_perm:[1,0,3,2] row_mask:0xf bank_mask:0xf
	s_nop 1
	v_perm_b32 v176, v176, v250, v102
	v_perm_b32 v178, v178, v251, v102
	s_mov_b32 vcc_lo, 0x33333333
	s_mov_b32 vcc_hi, 0x33333333
	v_cndmask_b32_dpp v194, v178, v176, vcc quad_perm:[2,3,0,1] row_mask:0xf bank_mask:0xf
	s_not_b64 vcc, vcc
	v_cndmask_b32_dpp v195, v176, v178, vcc quad_perm:[2,3,0,1] row_mask:0xf bank_mask:0xf
	v_or_b32_e32 v176, 16, v101
	v_mul_u32_u24_e32 v176, s8, v176
	v_sub_u32_e32 v176, v176, v100
	v_lshlrev_b32_e32 v176, 1, v176
	v_mov_b32_e32 v177, 0
	v_lshl_add_u64 v[250:251], v[98:99], 0, v[176:177]
	global_store_dwordx2 v[250:251], v[194:195], off
	v_bfe_u32 v176, v86, 16, 1
	v_bfe_u32 v177, v87, 16, 1
	v_bfe_u32 v178, v88, 16, 1
	v_bfe_u32 v179, v89, 16, 1
	v_add3_u32 v176, v86, v176, s31
	v_add3_u32 v177, v87, v177, s31
	v_add3_u32 v178, v88, v178, s31
	v_add3_u32 v179, v89, v179, s31
	s_mov_b32 vcc_lo, 0x55555555
	s_mov_b32 vcc_hi, 0x55555555
	v_cndmask_b32_dpp v250, v177, v176, vcc quad_perm:[1,0,3,2] row_mask:0xf bank_mask:0xf
	v_cndmask_b32_dpp v251, v179, v178, vcc quad_perm:[1,0,3,2] row_mask:0xf bank_mask:0xf
	s_not_b64 vcc, vcc
	v_cndmask_b32_dpp v176, v176, v177, vcc quad_perm:[1,0,3,2] row_mask:0xf bank_mask:0xf
	v_cndmask_b32_dpp v178, v178, v179, vcc quad_perm:[1,0,3,2] row_mask:0xf bank_mask:0xf
	s_nop 1
	v_perm_b32 v176, v176, v250, v102
	v_perm_b32 v178, v178, v251, v102
	s_mov_b32 vcc_lo, 0x33333333
	s_mov_b32 vcc_hi, 0x33333333
	v_cndmask_b32_dpp v194, v178, v176, vcc quad_perm:[2,3,0,1] row_mask:0xf bank_mask:0xf
	s_not_b64 vcc, vcc
	v_cndmask_b32_dpp v195, v176, v178, vcc quad_perm:[2,3,0,1] row_mask:0xf bank_mask:0xf
	v_or_b32_e32 v176, 32, v101
	v_mul_u32_u24_e32 v176, s8, v176
	v_sub_u32_e32 v176, v176, v100
	v_lshlrev_b32_e32 v176, 1, v176
	v_mov_b32_e32 v177, 0
	v_lshl_add_u64 v[250:251], v[98:99], 0, v[176:177]
	global_store_dwordx2 v[250:251], v[194:195], off
	v_bfe_u32 v176, v82, 16, 1
	v_bfe_u32 v177, v83, 16, 1
	v_bfe_u32 v178, v84, 16, 1
	v_bfe_u32 v179, v85, 16, 1
	v_add3_u32 v176, v82, v176, s31
	v_add3_u32 v177, v83, v177, s31
	v_add3_u32 v178, v84, v178, s31
	v_add3_u32 v179, v85, v179, s31
	s_mov_b32 vcc_lo, 0x55555555
	s_mov_b32 vcc_hi, 0x55555555
	v_cndmask_b32_dpp v250, v177, v176, vcc quad_perm:[1,0,3,2] row_mask:0xf bank_mask:0xf
	v_cndmask_b32_dpp v251, v179, v178, vcc quad_perm:[1,0,3,2] row_mask:0xf bank_mask:0xf
	s_not_b64 vcc, vcc
	v_cndmask_b32_dpp v176, v176, v177, vcc quad_perm:[1,0,3,2] row_mask:0xf bank_mask:0xf
	v_cndmask_b32_dpp v178, v178, v179, vcc quad_perm:[1,0,3,2] row_mask:0xf bank_mask:0xf
	s_nop 1
	v_perm_b32 v176, v176, v250, v102
	v_perm_b32 v178, v178, v251, v102
	s_mov_b32 vcc_lo, 0x33333333
	s_mov_b32 vcc_hi, 0x33333333
	v_cndmask_b32_dpp v194, v178, v176, vcc quad_perm:[2,3,0,1] row_mask:0xf bank_mask:0xf
	s_not_b64 vcc, vcc
	v_cndmask_b32_dpp v195, v176, v178, vcc quad_perm:[2,3,0,1] row_mask:0xf bank_mask:0xf
	v_or_b32_e32 v176, 48, v101
	v_mul_u32_u24_e32 v176, s8, v176
	v_sub_u32_e32 v176, v176, v100
	v_lshlrev_b32_e32 v176, 1, v176
	v_mov_b32_e32 v177, 0
	v_lshl_add_u64 v[250:251], v[98:99], 0, v[176:177]
	global_store_dwordx2 v[250:251], v[194:195], off

.LBB0_1456:
	v_lshlrev_b32_e32 v86, 1, v82
	v_mov_b32_e32 v87, v1
	v_lshl_add_u64 v[86:87], v[88:89], 0, v[86:87]
	v_and_b32_e32 v83, 3, v166
	v_add_u32_e32 v85, v148, v83
	v_mov_b32_e32 v88, 0x7060302
	v_bfe_u32 v176, v78, 16, 1
	v_bfe_u32 v177, v79, 16, 1
	v_bfe_u32 v178, v80, 16, 1
	v_bfe_u32 v179, v81, 16, 1
	v_add3_u32 v176, v78, v176, s31
	v_add3_u32 v177, v79, v177, s31
	v_add3_u32 v178, v80, v178, s31
	v_add3_u32 v179, v81, v179, s31
	s_mov_b32 vcc_lo, 0x55555555
	s_mov_b32 vcc_hi, 0x55555555
	v_cndmask_b32_dpp v250, v177, v176, vcc quad_perm:[1,0,3,2] row_mask:0xf bank_mask:0xf
	v_cndmask_b32_dpp v251, v179, v178, vcc quad_perm:[1,0,3,2] row_mask:0xf bank_mask:0xf
	s_not_b64 vcc, vcc
	v_cndmask_b32_dpp v176, v176, v177, vcc quad_perm:[1,0,3,2] row_mask:0xf bank_mask:0xf
	v_cndmask_b32_dpp v178, v178, v179, vcc quad_perm:[1,0,3,2] row_mask:0xf bank_mask:0xf
	s_nop 1
	v_perm_b32 v176, v176, v250, v88
	v_perm_b32 v178, v178, v251, v88
	s_mov_b32 vcc_lo, 0x33333333
	s_mov_b32 vcc_hi, 0x33333333
	v_cndmask_b32_dpp v194, v178, v176, vcc quad_perm:[2,3,0,1] row_mask:0xf bank_mask:0xf
	s_not_b64 vcc, vcc
	v_cndmask_b32_dpp v195, v176, v178, vcc quad_perm:[2,3,0,1] row_mask:0xf bank_mask:0xf
	v_mov_b32_e32 v176, v85
	v_mul_u32_u24_e32 v176, s8, v176
	v_sub_u32_e32 v176, v176, v83
	v_lshlrev_b32_e32 v176, 1, v176
	v_mov_b32_e32 v177, 0
	v_lshl_add_u64 v[250:251], v[86:87], 0, v[176:177]
	global_store_dwordx2 v[250:251], v[194:195], off
	v_bfe_u32 v176, v74, 16, 1
	v_bfe_u32 v177, v75, 16, 1
	v_bfe_u32 v178, v76, 16, 1
	v_bfe_u32 v179, v77, 16, 1
	v_add3_u32 v176, v74, v176, s31
	v_add3_u32 v177, v75, v177, s31
	v_add3_u32 v178, v76, v178, s31
	v_add3_u32 v179, v77, v179, s31
	s_mov_b32 vcc_lo, 0x55555555
	s_mov_b32 vcc_hi, 0x55555555
	v_cndmask_b32_dpp v250, v177, v176, vcc quad_perm:[1,0,3,2] row_mask:0xf bank_mask:0xf
	v_cndmask_b32_dpp v251, v179, v178, vcc quad_perm:[1,0,3,2] row_mask:0xf bank_mask:0xf
	s_not_b64 vcc, vcc
	v_cndmask_b32_dpp v176, v176, v177, vcc quad_perm:[1,0,3,2] row_mask:0xf bank_mask:0xf
	v_cndmask_b32_dpp v178, v178, v179, vcc quad_perm:[1,0,3,2] row_mask:0xf bank_mask:0xf
	s_nop 1
	v_perm_b32 v176, v176, v250, v88
	v_perm_b32 v178, v178, v251, v88
	s_mov_b32 vcc_lo, 0x33333333
	s_mov_b32 vcc_hi, 0x33333333
	v_cndmask_b32_dpp v194, v178, v176, vcc quad_perm:[2,3,0,1] row_mask:0xf bank_mask:0xf
	s_not_b64 vcc, vcc
	v_cndmask_b32_dpp v195, v176, v178, vcc quad_perm:[2,3,0,1] row_mask:0xf bank_mask:0xf
	v_or_b32_e32 v176, 16, v85
	v_mul_u32_u24_e32 v176, s8, v176
	v_sub_u32_e32 v176, v176, v83
	v_lshlrev_b32_e32 v176, 1, v176
	v_mov_b32_e32 v177, 0
	v_lshl_add_u64 v[250:251], v[86:87], 0, v[176:177]
	global_store_dwordx2 v[250:251], v[194:195], off
	v_bfe_u32 v176, v70, 16, 1
	v_bfe_u32 v177, v71, 16, 1
	v_bfe_u32 v178, v72, 16, 1
	v_bfe_u32 v179, v73, 16, 1
	v_add3_u32 v176, v70, v176, s31
	v_add3_u32 v177, v71, v177, s31
	v_add3_u32 v178, v72, v178, s31
	v_add3_u32 v179, v73, v179, s31
	s_mov_b32 vcc_lo, 0x55555555
	s_mov_b32 vcc_hi, 0x55555555
	v_cndmask_b32_dpp v250, v177, v176, vcc quad_perm:[1,0,3,2] row_mask:0xf bank_mask:0xf
	v_cndmask_b32_dpp v251, v179, v178, vcc quad_perm:[1,0,3,2] row_mask:0xf bank_mask:0xf
	s_not_b64 vcc, vcc
	v_cndmask_b32_dpp v176, v176, v177, vcc quad_perm:[1,0,3,2] row_mask:0xf bank_mask:0xf
	v_cndmask_b32_dpp v178, v178, v179, vcc quad_perm:[1,0,3,2] row_mask:0xf bank_mask:0xf
	s_nop 1
	v_perm_b32 v176, v176, v250, v88
	v_perm_b32 v178, v178, v251, v88
	s_mov_b32 vcc_lo, 0x33333333
	s_mov_b32 vcc_hi, 0x33333333
	v_cndmask_b32_dpp v194, v178, v176, vcc quad_perm:[2,3,0,1] row_mask:0xf bank_mask:0xf
	s_not_b64 vcc, vcc
	v_cndmask_b32_dpp v195, v176, v178, vcc quad_perm:[2,3,0,1] row_mask:0xf bank_mask:0xf
	v_or_b32_e32 v176, 32, v85
	v_mul_u32_u24_e32 v176, s8, v176
	v_sub_u32_e32 v176, v176, v83
	v_lshlrev_b32_e32 v176, 1, v176
	v_mov_b32_e32 v177, 0
	v_lshl_add_u64 v[250:251], v[86:87], 0, v[176:177]
	global_store_dwordx2 v[250:251], v[194:195], off
	v_bfe_u32 v176, v66, 16, 1
	v_bfe_u32 v177, v67, 16, 1
	v_bfe_u32 v178, v68, 16, 1
	v_bfe_u32 v179, v69, 16, 1
	v_add3_u32 v176, v66, v176, s31
	v_add3_u32 v177, v67, v177, s31
	v_add3_u32 v178, v68, v178, s31
	v_add3_u32 v179, v69, v179, s31
	s_mov_b32 vcc_lo, 0x55555555
	s_mov_b32 vcc_hi, 0x55555555
	v_cndmask_b32_dpp v250, v177, v176, vcc quad_perm:[1,0,3,2] row_mask:0xf bank_mask:0xf
	v_cndmask_b32_dpp v251, v179, v178, vcc quad_perm:[1,0,3,2] row_mask:0xf bank_mask:0xf
	s_not_b64 vcc, vcc
	v_cndmask_b32_dpp v176, v176, v177, vcc quad_perm:[1,0,3,2] row_mask:0xf bank_mask:0xf
	v_cndmask_b32_dpp v178, v178, v179, vcc quad_perm:[1,0,3,2] row_mask:0xf bank_mask:0xf
	s_nop 1
	v_perm_b32 v176, v176, v250, v88
	v_perm_b32 v178, v178, v251, v88
	s_mov_b32 vcc_lo, 0x33333333
	s_mov_b32 vcc_hi, 0x33333333
	v_cndmask_b32_dpp v194, v178, v176, vcc quad_perm:[2,3,0,1] row_mask:0xf bank_mask:0xf
	s_not_b64 vcc, vcc
	v_cndmask_b32_dpp v195, v176, v178, vcc quad_perm:[2,3,0,1] row_mask:0xf bank_mask:0xf
	v_or_b32_e32 v176, 48, v85
	v_mul_u32_u24_e32 v176, s8, v176
	v_sub_u32_e32 v176, v176, v83
	v_lshlrev_b32_e32 v176, 1, v176
	v_mov_b32_e32 v177, 0
	v_lshl_add_u64 v[250:251], v[86:87], 0, v[176:177]
	global_store_dwordx2 v[250:251], v[194:195], off
	s_mov_b64 s[0:1], 0

.LBB0_1477:
	v_lshlrev_b32_e32 v82, 1, v82
	v_mov_b32_e32 v83, v1
	v_lshl_add_u64 v[82:83], v[86:87], 0, v[82:83]
	v_and_b32_e32 v84, 3, v166
	v_add_u32_e32 v85, v148, v84
	v_mov_b32_e32 v86, 0x7060302
	v_bfe_u32 v176, v78, 16, 1
	v_bfe_u32 v177, v79, 16, 1
	v_bfe_u32 v178, v80, 16, 1
	v_bfe_u32 v179, v81, 16, 1
	v_add3_u32 v176, v78, v176, s31
	v_add3_u32 v177, v79, v177, s31
	v_add3_u32 v178, v80, v178, s31
	v_add3_u32 v179, v81, v179, s31
	s_mov_b32 vcc_lo, 0x55555555
	s_mov_b32 vcc_hi, 0x55555555
	v_cndmask_b32_dpp v250, v177, v176, vcc quad_perm:[1,0,3,2] row_mask:0xf bank_mask:0xf
	v_cndmask_b32_dpp v251, v179, v178, vcc quad_perm:[1,0,3,2] row_mask:0xf bank_mask:0xf
	s_not_b64 vcc, vcc
	v_cndmask_b32_dpp v176, v176, v177, vcc quad_perm:[1,0,3,2] row_mask:0xf bank_mask:0xf
	v_cndmask_b32_dpp v178, v178, v179, vcc quad_perm:[1,0,3,2] row_mask:0xf bank_mask:0xf
	s_nop 1
	v_perm_b32 v176, v176, v250, v86
	v_perm_b32 v178, v178, v251, v86
	s_mov_b32 vcc_lo, 0x33333333
	s_mov_b32 vcc_hi, 0x33333333
	v_cndmask_b32_dpp v194, v178, v176, vcc quad_perm:[2,3,0,1] row_mask:0xf bank_mask:0xf
	s_not_b64 vcc, vcc
	v_cndmask_b32_dpp v195, v176, v178, vcc quad_perm:[2,3,0,1] row_mask:0xf bank_mask:0xf
	v_mov_b32_e32 v176, v85
	v_mul_u32_u24_e32 v176, s8, v176
	v_sub_u32_e32 v176, v176, v84
	v_lshlrev_b32_e32 v176, 1, v176
	v_mov_b32_e32 v177, 0
	v_lshl_add_u64 v[250:251], v[82:83], 0, v[176:177]
	global_store_dwordx2 v[250:251], v[194:195], off
	v_bfe_u32 v176, v74, 16, 1
	v_bfe_u32 v177, v75, 16, 1
	v_bfe_u32 v178, v76, 16, 1
	v_bfe_u32 v179, v77, 16, 1
	v_add3_u32 v176, v74, v176, s31
	v_add3_u32 v177, v75, v177, s31
	v_add3_u32 v178, v76, v178, s31
	v_add3_u32 v179, v77, v179, s31
	s_mov_b32 vcc_lo, 0x55555555
	s_mov_b32 vcc_hi, 0x55555555
	v_cndmask_b32_dpp v250, v177, v176, vcc quad_perm:[1,0,3,2] row_mask:0xf bank_mask:0xf
	v_cndmask_b32_dpp v251, v179, v178, vcc quad_perm:[1,0,3,2] row_mask:0xf bank_mask:0xf
	s_not_b64 vcc, vcc
	v_cndmask_b32_dpp v176, v176, v177, vcc quad_perm:[1,0,3,2] row_mask:0xf bank_mask:0xf
	v_cndmask_b32_dpp v178, v178, v179, vcc quad_perm:[1,0,3,2] row_mask:0xf bank_mask:0xf
	s_nop 1
	v_perm_b32 v176, v176, v250, v86
	v_perm_b32 v178, v178, v251, v86
	s_mov_b32 vcc_lo, 0x33333333
	s_mov_b32 vcc_hi, 0x33333333
	v_cndmask_b32_dpp v194, v178, v176, vcc quad_perm:[2,3,0,1] row_mask:0xf bank_mask:0xf
	s_not_b64 vcc, vcc
	v_cndmask_b32_dpp v195, v176, v178, vcc quad_perm:[2,3,0,1] row_mask:0xf bank_mask:0xf
	v_or_b32_e32 v176, 16, v85
	v_mul_u32_u24_e32 v176, s8, v176
	v_sub_u32_e32 v176, v176, v84
	v_lshlrev_b32_e32 v176, 1, v176
	v_mov_b32_e32 v177, 0
	v_lshl_add_u64 v[250:251], v[82:83], 0, v[176:177]
	global_store_dwordx2 v[250:251], v[194:195], off
	v_bfe_u32 v176, v70, 16, 1
	v_bfe_u32 v177, v71, 16, 1
	v_bfe_u32 v178, v72, 16, 1
	v_bfe_u32 v179, v73, 16, 1
	v_add3_u32 v176, v70, v176, s31
	v_add3_u32 v177, v71, v177, s31
	v_add3_u32 v178, v72, v178, s31
	v_add3_u32 v179, v73, v179, s31
	s_mov_b32 vcc_lo, 0x55555555
	s_mov_b32 vcc_hi, 0x55555555
	v_cndmask_b32_dpp v250, v177, v176, vcc quad_perm:[1,0,3,2] row_mask:0xf bank_mask:0xf
	v_cndmask_b32_dpp v251, v179, v178, vcc quad_perm:[1,0,3,2] row_mask:0xf bank_mask:0xf
	s_not_b64 vcc, vcc
	v_cndmask_b32_dpp v176, v176, v177, vcc quad_perm:[1,0,3,2] row_mask:0xf bank_mask:0xf
	v_cndmask_b32_dpp v178, v178, v179, vcc quad_perm:[1,0,3,2] row_mask:0xf bank_mask:0xf
	s_nop 1
	v_perm_b32 v176, v176, v250, v86
	v_perm_b32 v178, v178, v251, v86
	s_mov_b32 vcc_lo, 0x33333333
	s_mov_b32 vcc_hi, 0x33333333
	v_cndmask_b32_dpp v194, v178, v176, vcc quad_perm:[2,3,0,1] row_mask:0xf bank_mask:0xf
	s_not_b64 vcc, vcc
	v_cndmask_b32_dpp v195, v176, v178, vcc quad_perm:[2,3,0,1] row_mask:0xf bank_mask:0xf
	v_or_b32_e32 v176, 32, v85
	v_mul_u32_u24_e32 v176, s8, v176
	v_sub_u32_e32 v176, v176, v84
	v_lshlrev_b32_e32 v176, 1, v176
	v_mov_b32_e32 v177, 0
	v_lshl_add_u64 v[250:251], v[82:83], 0, v[176:177]
	global_store_dwordx2 v[250:251], v[194:195], off
	v_bfe_u32 v176, v66, 16, 1
	v_bfe_u32 v177, v67, 16, 1
	v_bfe_u32 v178, v68, 16, 1
	v_bfe_u32 v179, v69, 16, 1
	v_add3_u32 v176, v66, v176, s31
	v_add3_u32 v177, v67, v177, s31
	v_add3_u32 v178, v68, v178, s31
	v_add3_u32 v179, v69, v179, s31
	s_mov_b32 vcc_lo, 0x55555555
	s_mov_b32 vcc_hi, 0x55555555
	v_cndmask_b32_dpp v250, v177, v176, vcc quad_perm:[1,0,3,2] row_mask:0xf bank_mask:0xf
	v_cndmask_b32_dpp v251, v179, v178, vcc quad_perm:[1,0,3,2] row_mask:0xf bank_mask:0xf
	s_not_b64 vcc, vcc
	v_cndmask_b32_dpp v176, v176, v177, vcc quad_perm:[1,0,3,2] row_mask:0xf bank_mask:0xf
	v_cndmask_b32_dpp v178, v178, v179, vcc quad_perm:[1,0,3,2] row_mask:0xf bank_mask:0xf
	s_nop 1
	v_perm_b32 v176, v176, v250, v86
	v_perm_b32 v178, v178, v251, v86
	s_mov_b32 vcc_lo, 0x33333333
	s_mov_b32 vcc_hi, 0x33333333
	v_cndmask_b32_dpp v194, v178, v176, vcc quad_perm:[2,3,0,1] row_mask:0xf bank_mask:0xf
	s_not_b64 vcc, vcc
	v_cndmask_b32_dpp v195, v176, v178, vcc quad_perm:[2,3,0,1] row_mask:0xf bank_mask:0xf
	v_or_b32_e32 v176, 48, v85
	v_mul_u32_u24_e32 v176, s8, v176
	v_sub_u32_e32 v176, v176, v84
	v_lshlrev_b32_e32 v176, 1, v176
	v_mov_b32_e32 v177, 0
	v_lshl_add_u64 v[250:251], v[82:83], 0, v[176:177]
	global_store_dwordx2 v[250:251], v[194:195], off

.LBB0_1503:
	v_lshlrev_b32_e32 v70, 1, v66
	v_mov_b32_e32 v71, v1
	v_lshl_add_u64 v[70:71], v[72:73], 0, v[70:71]
	v_and_b32_e32 v67, 3, v166
	v_add_u32_e32 v69, v148, v67
	v_mov_b32_e32 v72, 0x7060302
	v_bfe_u32 v176, v62, 16, 1
	v_bfe_u32 v177, v63, 16, 1
	v_bfe_u32 v178, v64, 16, 1
	v_bfe_u32 v179, v65, 16, 1
	v_add3_u32 v176, v62, v176, s31
	v_add3_u32 v177, v63, v177, s31
	v_add3_u32 v178, v64, v178, s31
	v_add3_u32 v179, v65, v179, s31
	s_mov_b32 vcc_lo, 0x55555555
	s_mov_b32 vcc_hi, 0x55555555
	v_cndmask_b32_dpp v250, v177, v176, vcc quad_perm:[1,0,3,2] row_mask:0xf bank_mask:0xf
	v_cndmask_b32_dpp v251, v179, v178, vcc quad_perm:[1,0,3,2] row_mask:0xf bank_mask:0xf
	s_not_b64 vcc, vcc
	v_cndmask_b32_dpp v176, v176, v177, vcc quad_perm:[1,0,3,2] row_mask:0xf bank_mask:0xf
	v_cndmask_b32_dpp v178, v178, v179, vcc quad_perm:[1,0,3,2] row_mask:0xf bank_mask:0xf
	s_nop 1
	v_perm_b32 v176, v176, v250, v72
	v_perm_b32 v178, v178, v251, v72
	s_mov_b32 vcc_lo, 0x33333333
	s_mov_b32 vcc_hi, 0x33333333
	v_cndmask_b32_dpp v194, v178, v176, vcc quad_perm:[2,3,0,1] row_mask:0xf bank_mask:0xf
	s_not_b64 vcc, vcc
	v_cndmask_b32_dpp v195, v176, v178, vcc quad_perm:[2,3,0,1] row_mask:0xf bank_mask:0xf
	v_mov_b32_e32 v176, v69
	v_mul_u32_u24_e32 v176, s8, v176
	v_sub_u32_e32 v176, v176, v67
	v_lshlrev_b32_e32 v176, 1, v176
	v_mov_b32_e32 v177, 0
	v_lshl_add_u64 v[250:251], v[70:71], 0, v[176:177]
	global_store_dwordx2 v[250:251], v[194:195], off
	v_bfe_u32 v176, v58, 16, 1
	v_bfe_u32 v177, v59, 16, 1
	v_bfe_u32 v178, v60, 16, 1
	v_bfe_u32 v179, v61, 16, 1
	v_add3_u32 v176, v58, v176, s31
	v_add3_u32 v177, v59, v177, s31
	v_add3_u32 v178, v60, v178, s31
	v_add3_u32 v179, v61, v179, s31
	s_mov_b32 vcc_lo, 0x55555555
	s_mov_b32 vcc_hi, 0x55555555
	v_cndmask_b32_dpp v250, v177, v176, vcc quad_perm:[1,0,3,2] row_mask:0xf bank_mask:0xf
	v_cndmask_b32_dpp v251, v179, v178, vcc quad_perm:[1,0,3,2] row_mask:0xf bank_mask:0xf
	s_not_b64 vcc, vcc
	v_cndmask_b32_dpp v176, v176, v177, vcc quad_perm:[1,0,3,2] row_mask:0xf bank_mask:0xf
	v_cndmask_b32_dpp v178, v178, v179, vcc quad_perm:[1,0,3,2] row_mask:0xf bank_mask:0xf
	s_nop 1
	v_perm_b32 v176, v176, v250, v72
	v_perm_b32 v178, v178, v251, v72
	s_mov_b32 vcc_lo, 0x33333333
	s_mov_b32 vcc_hi, 0x33333333
	v_cndmask_b32_dpp v194, v178, v176, vcc quad_perm:[2,3,0,1] row_mask:0xf bank_mask:0xf
	s_not_b64 vcc, vcc
	v_cndmask_b32_dpp v195, v176, v178, vcc quad_perm:[2,3,0,1] row_mask:0xf bank_mask:0xf
	v_or_b32_e32 v176, 16, v69
	v_mul_u32_u24_e32 v176, s8, v176
	v_sub_u32_e32 v176, v176, v67
	v_lshlrev_b32_e32 v176, 1, v176
	v_mov_b32_e32 v177, 0
	v_lshl_add_u64 v[250:251], v[70:71], 0, v[176:177]
	global_store_dwordx2 v[250:251], v[194:195], off
	v_bfe_u32 v176, v54, 16, 1
	v_bfe_u32 v177, v55, 16, 1
	v_bfe_u32 v178, v56, 16, 1
	v_bfe_u32 v179, v57, 16, 1
	v_add3_u32 v176, v54, v176, s31
	v_add3_u32 v177, v55, v177, s31
	v_add3_u32 v178, v56, v178, s31
	v_add3_u32 v179, v57, v179, s31
	s_mov_b32 vcc_lo, 0x55555555
	s_mov_b32 vcc_hi, 0x55555555
	v_cndmask_b32_dpp v250, v177, v176, vcc quad_perm:[1,0,3,2] row_mask:0xf bank_mask:0xf
	v_cndmask_b32_dpp v251, v179, v178, vcc quad_perm:[1,0,3,2] row_mask:0xf bank_mask:0xf
	s_not_b64 vcc, vcc
	v_cndmask_b32_dpp v176, v176, v177, vcc quad_perm:[1,0,3,2] row_mask:0xf bank_mask:0xf
	v_cndmask_b32_dpp v178, v178, v179, vcc quad_perm:[1,0,3,2] row_mask:0xf bank_mask:0xf
	s_nop 1
	v_perm_b32 v176, v176, v250, v72
	v_perm_b32 v178, v178, v251, v72
	s_mov_b32 vcc_lo, 0x33333333
	s_mov_b32 vcc_hi, 0x33333333
	v_cndmask_b32_dpp v194, v178, v176, vcc quad_perm:[2,3,0,1] row_mask:0xf bank_mask:0xf
	s_not_b64 vcc, vcc
	v_cndmask_b32_dpp v195, v176, v178, vcc quad_perm:[2,3,0,1] row_mask:0xf bank_mask:0xf
	v_or_b32_e32 v176, 32, v69
	v_mul_u32_u24_e32 v176, s8, v176
	v_sub_u32_e32 v176, v176, v67
	v_lshlrev_b32_e32 v176, 1, v176
	v_mov_b32_e32 v177, 0
	v_lshl_add_u64 v[250:251], v[70:71], 0, v[176:177]
	global_store_dwordx2 v[250:251], v[194:195], off
	v_bfe_u32 v176, v50, 16, 1
	v_bfe_u32 v177, v51, 16, 1
	v_bfe_u32 v178, v52, 16, 1
	v_bfe_u32 v179, v53, 16, 1
	v_add3_u32 v176, v50, v176, s31
	v_add3_u32 v177, v51, v177, s31
	v_add3_u32 v178, v52, v178, s31
	v_add3_u32 v179, v53, v179, s31
	s_mov_b32 vcc_lo, 0x55555555
	s_mov_b32 vcc_hi, 0x55555555
	v_cndmask_b32_dpp v250, v177, v176, vcc quad_perm:[1,0,3,2] row_mask:0xf bank_mask:0xf
	v_cndmask_b32_dpp v251, v179, v178, vcc quad_perm:[1,0,3,2] row_mask:0xf bank_mask:0xf
	s_not_b64 vcc, vcc
	v_cndmask_b32_dpp v176, v176, v177, vcc quad_perm:[1,0,3,2] row_mask:0xf bank_mask:0xf
	v_cndmask_b32_dpp v178, v178, v179, vcc quad_perm:[1,0,3,2] row_mask:0xf bank_mask:0xf
	s_nop 1
	v_perm_b32 v176, v176, v250, v72
	v_perm_b32 v178, v178, v251, v72
	s_mov_b32 vcc_lo, 0x33333333
	s_mov_b32 vcc_hi, 0x33333333
	v_cndmask_b32_dpp v194, v178, v176, vcc quad_perm:[2,3,0,1] row_mask:0xf bank_mask:0xf
	s_not_b64 vcc, vcc
	v_cndmask_b32_dpp v195, v176, v178, vcc quad_perm:[2,3,0,1] row_mask:0xf bank_mask:0xf
	v_or_b32_e32 v176, 48, v69
	v_mul_u32_u24_e32 v176, s8, v176
	v_sub_u32_e32 v176, v176, v67
	v_lshlrev_b32_e32 v176, 1, v176
	v_mov_b32_e32 v177, 0
	v_lshl_add_u64 v[250:251], v[70:71], 0, v[176:177]
	global_store_dwordx2 v[250:251], v[194:195], off
	s_mov_b64 s[0:1], 0

.LBB0_1524:
	v_lshlrev_b32_e32 v66, 1, v66
	v_mov_b32_e32 v67, v1
	v_lshl_add_u64 v[66:67], v[70:71], 0, v[66:67]
	v_and_b32_e32 v68, 3, v166
	v_add_u32_e32 v69, v148, v68
	v_mov_b32_e32 v70, 0x7060302
	v_bfe_u32 v176, v62, 16, 1
	v_bfe_u32 v177, v63, 16, 1
	v_bfe_u32 v178, v64, 16, 1
	v_bfe_u32 v179, v65, 16, 1
	v_add3_u32 v176, v62, v176, s31
	v_add3_u32 v177, v63, v177, s31
	v_add3_u32 v178, v64, v178, s31
	v_add3_u32 v179, v65, v179, s31
	s_mov_b32 vcc_lo, 0x55555555
	s_mov_b32 vcc_hi, 0x55555555
	v_cndmask_b32_dpp v250, v177, v176, vcc quad_perm:[1,0,3,2] row_mask:0xf bank_mask:0xf
	v_cndmask_b32_dpp v251, v179, v178, vcc quad_perm:[1,0,3,2] row_mask:0xf bank_mask:0xf
	s_not_b64 vcc, vcc
	v_cndmask_b32_dpp v176, v176, v177, vcc quad_perm:[1,0,3,2] row_mask:0xf bank_mask:0xf
	v_cndmask_b32_dpp v178, v178, v179, vcc quad_perm:[1,0,3,2] row_mask:0xf bank_mask:0xf
	s_nop 1
	v_perm_b32 v176, v176, v250, v70
	v_perm_b32 v178, v178, v251, v70
	s_mov_b32 vcc_lo, 0x33333333
	s_mov_b32 vcc_hi, 0x33333333
	v_cndmask_b32_dpp v194, v178, v176, vcc quad_perm:[2,3,0,1] row_mask:0xf bank_mask:0xf
	s_not_b64 vcc, vcc
	v_cndmask_b32_dpp v195, v176, v178, vcc quad_perm:[2,3,0,1] row_mask:0xf bank_mask:0xf
	v_mov_b32_e32 v176, v69
	v_mul_u32_u24_e32 v176, s8, v176
	v_sub_u32_e32 v176, v176, v68
	v_lshlrev_b32_e32 v176, 1, v176
	v_mov_b32_e32 v177, 0
	v_lshl_add_u64 v[250:251], v[66:67], 0, v[176:177]
	global_store_dwordx2 v[250:251], v[194:195], off
	v_bfe_u32 v176, v58, 16, 1
	v_bfe_u32 v177, v59, 16, 1
	v_bfe_u32 v178, v60, 16, 1
	v_bfe_u32 v179, v61, 16, 1
	v_add3_u32 v176, v58, v176, s31
	v_add3_u32 v177, v59, v177, s31
	v_add3_u32 v178, v60, v178, s31
	v_add3_u32 v179, v61, v179, s31
	s_mov_b32 vcc_lo, 0x55555555
	s_mov_b32 vcc_hi, 0x55555555
	v_cndmask_b32_dpp v250, v177, v176, vcc quad_perm:[1,0,3,2] row_mask:0xf bank_mask:0xf
	v_cndmask_b32_dpp v251, v179, v178, vcc quad_perm:[1,0,3,2] row_mask:0xf bank_mask:0xf
	s_not_b64 vcc, vcc
	v_cndmask_b32_dpp v176, v176, v177, vcc quad_perm:[1,0,3,2] row_mask:0xf bank_mask:0xf
	v_cndmask_b32_dpp v178, v178, v179, vcc quad_perm:[1,0,3,2] row_mask:0xf bank_mask:0xf
	s_nop 1
	v_perm_b32 v176, v176, v250, v70
	v_perm_b32 v178, v178, v251, v70
	s_mov_b32 vcc_lo, 0x33333333
	s_mov_b32 vcc_hi, 0x33333333
	v_cndmask_b32_dpp v194, v178, v176, vcc quad_perm:[2,3,0,1] row_mask:0xf bank_mask:0xf
	s_not_b64 vcc, vcc
	v_cndmask_b32_dpp v195, v176, v178, vcc quad_perm:[2,3,0,1] row_mask:0xf bank_mask:0xf
	v_or_b32_e32 v176, 16, v69
	v_mul_u32_u24_e32 v176, s8, v176
	v_sub_u32_e32 v176, v176, v68
	v_lshlrev_b32_e32 v176, 1, v176
	v_mov_b32_e32 v177, 0
	v_lshl_add_u64 v[250:251], v[66:67], 0, v[176:177]
	global_store_dwordx2 v[250:251], v[194:195], off
	v_bfe_u32 v176, v54, 16, 1
	v_bfe_u32 v177, v55, 16, 1
	v_bfe_u32 v178, v56, 16, 1
	v_bfe_u32 v179, v57, 16, 1
	v_add3_u32 v176, v54, v176, s31
	v_add3_u32 v177, v55, v177, s31
	v_add3_u32 v178, v56, v178, s31
	v_add3_u32 v179, v57, v179, s31
	s_mov_b32 vcc_lo, 0x55555555
	s_mov_b32 vcc_hi, 0x55555555
	v_cndmask_b32_dpp v250, v177, v176, vcc quad_perm:[1,0,3,2] row_mask:0xf bank_mask:0xf
	v_cndmask_b32_dpp v251, v179, v178, vcc quad_perm:[1,0,3,2] row_mask:0xf bank_mask:0xf
	s_not_b64 vcc, vcc
	v_cndmask_b32_dpp v176, v176, v177, vcc quad_perm:[1,0,3,2] row_mask:0xf bank_mask:0xf
	v_cndmask_b32_dpp v178, v178, v179, vcc quad_perm:[1,0,3,2] row_mask:0xf bank_mask:0xf
	s_nop 1
	v_perm_b32 v176, v176, v250, v70
	v_perm_b32 v178, v178, v251, v70
	s_mov_b32 vcc_lo, 0x33333333
	s_mov_b32 vcc_hi, 0x33333333
	v_cndmask_b32_dpp v194, v178, v176, vcc quad_perm:[2,3,0,1] row_mask:0xf bank_mask:0xf
	s_not_b64 vcc, vcc
	v_cndmask_b32_dpp v195, v176, v178, vcc quad_perm:[2,3,0,1] row_mask:0xf bank_mask:0xf
	v_or_b32_e32 v176, 32, v69
	v_mul_u32_u24_e32 v176, s8, v176
	v_sub_u32_e32 v176, v176, v68
	v_lshlrev_b32_e32 v176, 1, v176
	v_mov_b32_e32 v177, 0
	v_lshl_add_u64 v[250:251], v[66:67], 0, v[176:177]
	global_store_dwordx2 v[250:251], v[194:195], off
	v_bfe_u32 v176, v50, 16, 1
	v_bfe_u32 v177, v51, 16, 1
	v_bfe_u32 v178, v52, 16, 1
	v_bfe_u32 v179, v53, 16, 1
	v_add3_u32 v176, v50, v176, s31
	v_add3_u32 v177, v51, v177, s31
	v_add3_u32 v178, v52, v178, s31
	v_add3_u32 v179, v53, v179, s31
	s_mov_b32 vcc_lo, 0x55555555
	s_mov_b32 vcc_hi, 0x55555555
	v_cndmask_b32_dpp v250, v177, v176, vcc quad_perm:[1,0,3,2] row_mask:0xf bank_mask:0xf
	v_cndmask_b32_dpp v251, v179, v178, vcc quad_perm:[1,0,3,2] row_mask:0xf bank_mask:0xf
	s_not_b64 vcc, vcc
	v_cndmask_b32_dpp v176, v176, v177, vcc quad_perm:[1,0,3,2] row_mask:0xf bank_mask:0xf
	v_cndmask_b32_dpp v178, v178, v179, vcc quad_perm:[1,0,3,2] row_mask:0xf bank_mask:0xf
	s_nop 1
	v_perm_b32 v176, v176, v250, v70
	v_perm_b32 v178, v178, v251, v70
	s_mov_b32 vcc_lo, 0x33333333
	s_mov_b32 vcc_hi, 0x33333333
	v_cndmask_b32_dpp v194, v178, v176, vcc quad_perm:[2,3,0,1] row_mask:0xf bank_mask:0xf
	s_not_b64 vcc, vcc
	v_cndmask_b32_dpp v195, v176, v178, vcc quad_perm:[2,3,0,1] row_mask:0xf bank_mask:0xf
	v_or_b32_e32 v176, 48, v69
	v_mul_u32_u24_e32 v176, s8, v176
	v_sub_u32_e32 v176, v176, v68
	v_lshlrev_b32_e32 v176, 1, v176
	v_mov_b32_e32 v177, 0
	v_lshl_add_u64 v[250:251], v[66:67], 0, v[176:177]
	global_store_dwordx2 v[250:251], v[194:195], off

.LBB0_1550:
	v_lshlrev_b32_e32 v54, 1, v50
	v_mov_b32_e32 v55, v1
	v_lshl_add_u64 v[54:55], v[56:57], 0, v[54:55]
	v_and_b32_e32 v51, 3, v166
	v_add_u32_e32 v53, v148, v51
	v_mov_b32_e32 v56, 0x7060302
	v_bfe_u32 v176, v46, 16, 1
	v_bfe_u32 v177, v47, 16, 1
	v_bfe_u32 v178, v48, 16, 1
	v_bfe_u32 v179, v49, 16, 1
	v_add3_u32 v176, v46, v176, s31
	v_add3_u32 v177, v47, v177, s31
	v_add3_u32 v178, v48, v178, s31
	v_add3_u32 v179, v49, v179, s31
	s_mov_b32 vcc_lo, 0x55555555
	s_mov_b32 vcc_hi, 0x55555555
	v_cndmask_b32_dpp v250, v177, v176, vcc quad_perm:[1,0,3,2] row_mask:0xf bank_mask:0xf
	v_cndmask_b32_dpp v251, v179, v178, vcc quad_perm:[1,0,3,2] row_mask:0xf bank_mask:0xf
	s_not_b64 vcc, vcc
	v_cndmask_b32_dpp v176, v176, v177, vcc quad_perm:[1,0,3,2] row_mask:0xf bank_mask:0xf
	v_cndmask_b32_dpp v178, v178, v179, vcc quad_perm:[1,0,3,2] row_mask:0xf bank_mask:0xf
	s_nop 1
	v_perm_b32 v176, v176, v250, v56
	v_perm_b32 v178, v178, v251, v56
	s_mov_b32 vcc_lo, 0x33333333
	s_mov_b32 vcc_hi, 0x33333333
	v_cndmask_b32_dpp v194, v178, v176, vcc quad_perm:[2,3,0,1] row_mask:0xf bank_mask:0xf
	s_not_b64 vcc, vcc
	v_cndmask_b32_dpp v195, v176, v178, vcc quad_perm:[2,3,0,1] row_mask:0xf bank_mask:0xf
	v_mov_b32_e32 v176, v53
	v_mul_u32_u24_e32 v176, s8, v176
	v_sub_u32_e32 v176, v176, v51
	v_lshlrev_b32_e32 v176, 1, v176
	v_mov_b32_e32 v177, 0
	v_lshl_add_u64 v[250:251], v[54:55], 0, v[176:177]
	global_store_dwordx2 v[250:251], v[194:195], off
	v_bfe_u32 v176, v42, 16, 1
	v_bfe_u32 v177, v43, 16, 1
	v_bfe_u32 v178, v44, 16, 1
	v_bfe_u32 v179, v45, 16, 1
	v_add3_u32 v176, v42, v176, s31
	v_add3_u32 v177, v43, v177, s31
	v_add3_u32 v178, v44, v178, s31
	v_add3_u32 v179, v45, v179, s31
	s_mov_b32 vcc_lo, 0x55555555
	s_mov_b32 vcc_hi, 0x55555555
	v_cndmask_b32_dpp v250, v177, v176, vcc quad_perm:[1,0,3,2] row_mask:0xf bank_mask:0xf
	v_cndmask_b32_dpp v251, v179, v178, vcc quad_perm:[1,0,3,2] row_mask:0xf bank_mask:0xf
	s_not_b64 vcc, vcc
	v_cndmask_b32_dpp v176, v176, v177, vcc quad_perm:[1,0,3,2] row_mask:0xf bank_mask:0xf
	v_cndmask_b32_dpp v178, v178, v179, vcc quad_perm:[1,0,3,2] row_mask:0xf bank_mask:0xf
	s_nop 1
	v_perm_b32 v176, v176, v250, v56
	v_perm_b32 v178, v178, v251, v56
	s_mov_b32 vcc_lo, 0x33333333
	s_mov_b32 vcc_hi, 0x33333333
	v_cndmask_b32_dpp v194, v178, v176, vcc quad_perm:[2,3,0,1] row_mask:0xf bank_mask:0xf
	s_not_b64 vcc, vcc
	v_cndmask_b32_dpp v195, v176, v178, vcc quad_perm:[2,3,0,1] row_mask:0xf bank_mask:0xf
	v_or_b32_e32 v176, 16, v53
	v_mul_u32_u24_e32 v176, s8, v176
	v_sub_u32_e32 v176, v176, v51
	v_lshlrev_b32_e32 v176, 1, v176
	v_mov_b32_e32 v177, 0
	v_lshl_add_u64 v[250:251], v[54:55], 0, v[176:177]
	global_store_dwordx2 v[250:251], v[194:195], off
	v_bfe_u32 v176, v38, 16, 1
	v_bfe_u32 v177, v39, 16, 1
	v_bfe_u32 v178, v40, 16, 1
	v_bfe_u32 v179, v41, 16, 1
	v_add3_u32 v176, v38, v176, s31
	v_add3_u32 v177, v39, v177, s31
	v_add3_u32 v178, v40, v178, s31
	v_add3_u32 v179, v41, v179, s31
	s_mov_b32 vcc_lo, 0x55555555
	s_mov_b32 vcc_hi, 0x55555555
	v_cndmask_b32_dpp v250, v177, v176, vcc quad_perm:[1,0,3,2] row_mask:0xf bank_mask:0xf
	v_cndmask_b32_dpp v251, v179, v178, vcc quad_perm:[1,0,3,2] row_mask:0xf bank_mask:0xf
	s_not_b64 vcc, vcc
	v_cndmask_b32_dpp v176, v176, v177, vcc quad_perm:[1,0,3,2] row_mask:0xf bank_mask:0xf
	v_cndmask_b32_dpp v178, v178, v179, vcc quad_perm:[1,0,3,2] row_mask:0xf bank_mask:0xf
	s_nop 1
	v_perm_b32 v176, v176, v250, v56
	v_perm_b32 v178, v178, v251, v56
	s_mov_b32 vcc_lo, 0x33333333
	s_mov_b32 vcc_hi, 0x33333333
	v_cndmask_b32_dpp v194, v178, v176, vcc quad_perm:[2,3,0,1] row_mask:0xf bank_mask:0xf
	s_not_b64 vcc, vcc
	v_cndmask_b32_dpp v195, v176, v178, vcc quad_perm:[2,3,0,1] row_mask:0xf bank_mask:0xf
	v_or_b32_e32 v176, 32, v53
	v_mul_u32_u24_e32 v176, s8, v176
	v_sub_u32_e32 v176, v176, v51
	v_lshlrev_b32_e32 v176, 1, v176
	v_mov_b32_e32 v177, 0
	v_lshl_add_u64 v[250:251], v[54:55], 0, v[176:177]
	global_store_dwordx2 v[250:251], v[194:195], off
	v_bfe_u32 v176, v34, 16, 1
	v_bfe_u32 v177, v35, 16, 1
	v_bfe_u32 v178, v36, 16, 1
	v_bfe_u32 v179, v37, 16, 1
	v_add3_u32 v176, v34, v176, s31
	v_add3_u32 v177, v35, v177, s31
	v_add3_u32 v178, v36, v178, s31
	v_add3_u32 v179, v37, v179, s31
	s_mov_b32 vcc_lo, 0x55555555
	s_mov_b32 vcc_hi, 0x55555555
	v_cndmask_b32_dpp v250, v177, v176, vcc quad_perm:[1,0,3,2] row_mask:0xf bank_mask:0xf
	v_cndmask_b32_dpp v251, v179, v178, vcc quad_perm:[1,0,3,2] row_mask:0xf bank_mask:0xf
	s_not_b64 vcc, vcc
	v_cndmask_b32_dpp v176, v176, v177, vcc quad_perm:[1,0,3,2] row_mask:0xf bank_mask:0xf
	v_cndmask_b32_dpp v178, v178, v179, vcc quad_perm:[1,0,3,2] row_mask:0xf bank_mask:0xf
	s_nop 1
	v_perm_b32 v176, v176, v250, v56
	v_perm_b32 v178, v178, v251, v56
	s_mov_b32 vcc_lo, 0x33333333
	s_mov_b32 vcc_hi, 0x33333333
	v_cndmask_b32_dpp v194, v178, v176, vcc quad_perm:[2,3,0,1] row_mask:0xf bank_mask:0xf
	s_not_b64 vcc, vcc
	v_cndmask_b32_dpp v195, v176, v178, vcc quad_perm:[2,3,0,1] row_mask:0xf bank_mask:0xf
	v_or_b32_e32 v176, 48, v53
	v_mul_u32_u24_e32 v176, s8, v176
	v_sub_u32_e32 v176, v176, v51
	v_lshlrev_b32_e32 v176, 1, v176
	v_mov_b32_e32 v177, 0
	v_lshl_add_u64 v[250:251], v[54:55], 0, v[176:177]
	global_store_dwordx2 v[250:251], v[194:195], off
	s_mov_b64 s[0:1], 0

.LBB0_1571:
	v_lshlrev_b32_e32 v50, 1, v50
	v_mov_b32_e32 v51, v1
	v_lshl_add_u64 v[50:51], v[54:55], 0, v[50:51]
	v_and_b32_e32 v52, 3, v166
	v_add_u32_e32 v53, v148, v52
	v_mov_b32_e32 v54, 0x7060302
	v_bfe_u32 v176, v46, 16, 1
	v_bfe_u32 v177, v47, 16, 1
	v_bfe_u32 v178, v48, 16, 1
	v_bfe_u32 v179, v49, 16, 1
	v_add3_u32 v176, v46, v176, s31
	v_add3_u32 v177, v47, v177, s31
	v_add3_u32 v178, v48, v178, s31
	v_add3_u32 v179, v49, v179, s31
	s_mov_b32 vcc_lo, 0x55555555
	s_mov_b32 vcc_hi, 0x55555555
	v_cndmask_b32_dpp v250, v177, v176, vcc quad_perm:[1,0,3,2] row_mask:0xf bank_mask:0xf
	v_cndmask_b32_dpp v251, v179, v178, vcc quad_perm:[1,0,3,2] row_mask:0xf bank_mask:0xf
	s_not_b64 vcc, vcc
	v_cndmask_b32_dpp v176, v176, v177, vcc quad_perm:[1,0,3,2] row_mask:0xf bank_mask:0xf
	v_cndmask_b32_dpp v178, v178, v179, vcc quad_perm:[1,0,3,2] row_mask:0xf bank_mask:0xf
	s_nop 1
	v_perm_b32 v176, v176, v250, v54
	v_perm_b32 v178, v178, v251, v54
	s_mov_b32 vcc_lo, 0x33333333
	s_mov_b32 vcc_hi, 0x33333333
	v_cndmask_b32_dpp v194, v178, v176, vcc quad_perm:[2,3,0,1] row_mask:0xf bank_mask:0xf
	s_not_b64 vcc, vcc
	v_cndmask_b32_dpp v195, v176, v178, vcc quad_perm:[2,3,0,1] row_mask:0xf bank_mask:0xf
	v_mov_b32_e32 v176, v53
	v_mul_u32_u24_e32 v176, s8, v176
	v_sub_u32_e32 v176, v176, v52
	v_lshlrev_b32_e32 v176, 1, v176
	v_mov_b32_e32 v177, 0
	v_lshl_add_u64 v[250:251], v[50:51], 0, v[176:177]
	global_store_dwordx2 v[250:251], v[194:195], off
	v_bfe_u32 v176, v42, 16, 1
	v_bfe_u32 v177, v43, 16, 1
	v_bfe_u32 v178, v44, 16, 1
	v_bfe_u32 v179, v45, 16, 1
	v_add3_u32 v176, v42, v176, s31
	v_add3_u32 v177, v43, v177, s31
	v_add3_u32 v178, v44, v178, s31
	v_add3_u32 v179, v45, v179, s31
	s_mov_b32 vcc_lo, 0x55555555
	s_mov_b32 vcc_hi, 0x55555555
	v_cndmask_b32_dpp v250, v177, v176, vcc quad_perm:[1,0,3,2] row_mask:0xf bank_mask:0xf
	v_cndmask_b32_dpp v251, v179, v178, vcc quad_perm:[1,0,3,2] row_mask:0xf bank_mask:0xf
	s_not_b64 vcc, vcc
	v_cndmask_b32_dpp v176, v176, v177, vcc quad_perm:[1,0,3,2] row_mask:0xf bank_mask:0xf
	v_cndmask_b32_dpp v178, v178, v179, vcc quad_perm:[1,0,3,2] row_mask:0xf bank_mask:0xf
	s_nop 1
	v_perm_b32 v176, v176, v250, v54
	v_perm_b32 v178, v178, v251, v54
	s_mov_b32 vcc_lo, 0x33333333
	s_mov_b32 vcc_hi, 0x33333333
	v_cndmask_b32_dpp v194, v178, v176, vcc quad_perm:[2,3,0,1] row_mask:0xf bank_mask:0xf
	s_not_b64 vcc, vcc
	v_cndmask_b32_dpp v195, v176, v178, vcc quad_perm:[2,3,0,1] row_mask:0xf bank_mask:0xf
	v_or_b32_e32 v176, 16, v53
	v_mul_u32_u24_e32 v176, s8, v176
	v_sub_u32_e32 v176, v176, v52
	v_lshlrev_b32_e32 v176, 1, v176
	v_mov_b32_e32 v177, 0
	v_lshl_add_u64 v[250:251], v[50:51], 0, v[176:177]
	global_store_dwordx2 v[250:251], v[194:195], off
	v_bfe_u32 v176, v38, 16, 1
	v_bfe_u32 v177, v39, 16, 1
	v_bfe_u32 v178, v40, 16, 1
	v_bfe_u32 v179, v41, 16, 1
	v_add3_u32 v176, v38, v176, s31
	v_add3_u32 v177, v39, v177, s31
	v_add3_u32 v178, v40, v178, s31
	v_add3_u32 v179, v41, v179, s31
	s_mov_b32 vcc_lo, 0x55555555
	s_mov_b32 vcc_hi, 0x55555555
	v_cndmask_b32_dpp v250, v177, v176, vcc quad_perm:[1,0,3,2] row_mask:0xf bank_mask:0xf
	v_cndmask_b32_dpp v251, v179, v178, vcc quad_perm:[1,0,3,2] row_mask:0xf bank_mask:0xf
	s_not_b64 vcc, vcc
	v_cndmask_b32_dpp v176, v176, v177, vcc quad_perm:[1,0,3,2] row_mask:0xf bank_mask:0xf
	v_cndmask_b32_dpp v178, v178, v179, vcc quad_perm:[1,0,3,2] row_mask:0xf bank_mask:0xf
	s_nop 1
	v_perm_b32 v176, v176, v250, v54
	v_perm_b32 v178, v178, v251, v54
	s_mov_b32 vcc_lo, 0x33333333
	s_mov_b32 vcc_hi, 0x33333333
	v_cndmask_b32_dpp v194, v178, v176, vcc quad_perm:[2,3,0,1] row_mask:0xf bank_mask:0xf
	s_not_b64 vcc, vcc
	v_cndmask_b32_dpp v195, v176, v178, vcc quad_perm:[2,3,0,1] row_mask:0xf bank_mask:0xf
	v_or_b32_e32 v176, 32, v53
	v_mul_u32_u24_e32 v176, s8, v176
	v_sub_u32_e32 v176, v176, v52
	v_lshlrev_b32_e32 v176, 1, v176
	v_mov_b32_e32 v177, 0
	v_lshl_add_u64 v[250:251], v[50:51], 0, v[176:177]
	global_store_dwordx2 v[250:251], v[194:195], off
	v_bfe_u32 v176, v34, 16, 1
	v_bfe_u32 v177, v35, 16, 1
	v_bfe_u32 v178, v36, 16, 1
	v_bfe_u32 v179, v37, 16, 1
	v_add3_u32 v176, v34, v176, s31
	v_add3_u32 v177, v35, v177, s31
	v_add3_u32 v178, v36, v178, s31
	v_add3_u32 v179, v37, v179, s31
	s_mov_b32 vcc_lo, 0x55555555
	s_mov_b32 vcc_hi, 0x55555555
	v_cndmask_b32_dpp v250, v177, v176, vcc quad_perm:[1,0,3,2] row_mask:0xf bank_mask:0xf
	v_cndmask_b32_dpp v251, v179, v178, vcc quad_perm:[1,0,3,2] row_mask:0xf bank_mask:0xf
	s_not_b64 vcc, vcc
	v_cndmask_b32_dpp v176, v176, v177, vcc quad_perm:[1,0,3,2] row_mask:0xf bank_mask:0xf
	v_cndmask_b32_dpp v178, v178, v179, vcc quad_perm:[1,0,3,2] row_mask:0xf bank_mask:0xf
	s_nop 1
	v_perm_b32 v176, v176, v250, v54
	v_perm_b32 v178, v178, v251, v54
	s_mov_b32 vcc_lo, 0x33333333
	s_mov_b32 vcc_hi, 0x33333333
	v_cndmask_b32_dpp v194, v178, v176, vcc quad_perm:[2,3,0,1] row_mask:0xf bank_mask:0xf
	s_not_b64 vcc, vcc
	v_cndmask_b32_dpp v195, v176, v178, vcc quad_perm:[2,3,0,1] row_mask:0xf bank_mask:0xf
	v_or_b32_e32 v176, 48, v53
	v_mul_u32_u24_e32 v176, s8, v176
	v_sub_u32_e32 v176, v176, v52
	v_lshlrev_b32_e32 v176, 1, v176
	v_mov_b32_e32 v177, 0
	v_lshl_add_u64 v[250:251], v[50:51], 0, v[176:177]
	global_store_dwordx2 v[250:251], v[194:195], off

.LBB0_1597:
	v_lshlrev_b32_e32 v38, 1, v34
	v_mov_b32_e32 v39, v1
	v_lshl_add_u64 v[38:39], v[40:41], 0, v[38:39]
	v_and_b32_e32 v35, 3, v166
	v_add_u32_e32 v37, v148, v35
	v_mov_b32_e32 v40, 0x7060302
	v_bfe_u32 v176, v30, 16, 1
	v_bfe_u32 v177, v31, 16, 1
	v_bfe_u32 v178, v32, 16, 1
	v_bfe_u32 v179, v33, 16, 1
	v_add3_u32 v176, v30, v176, s31
	v_add3_u32 v177, v31, v177, s31
	v_add3_u32 v178, v32, v178, s31
	v_add3_u32 v179, v33, v179, s31
	s_mov_b32 vcc_lo, 0x55555555
	s_mov_b32 vcc_hi, 0x55555555
	v_cndmask_b32_dpp v250, v177, v176, vcc quad_perm:[1,0,3,2] row_mask:0xf bank_mask:0xf
	v_cndmask_b32_dpp v251, v179, v178, vcc quad_perm:[1,0,3,2] row_mask:0xf bank_mask:0xf
	s_not_b64 vcc, vcc
	v_cndmask_b32_dpp v176, v176, v177, vcc quad_perm:[1,0,3,2] row_mask:0xf bank_mask:0xf
	v_cndmask_b32_dpp v178, v178, v179, vcc quad_perm:[1,0,3,2] row_mask:0xf bank_mask:0xf
	s_nop 1
	v_perm_b32 v176, v176, v250, v40
	v_perm_b32 v178, v178, v251, v40
	s_mov_b32 vcc_lo, 0x33333333
	s_mov_b32 vcc_hi, 0x33333333
	v_cndmask_b32_dpp v194, v178, v176, vcc quad_perm:[2,3,0,1] row_mask:0xf bank_mask:0xf
	s_not_b64 vcc, vcc
	v_cndmask_b32_dpp v195, v176, v178, vcc quad_perm:[2,3,0,1] row_mask:0xf bank_mask:0xf
	v_mov_b32_e32 v176, v37
	v_mul_u32_u24_e32 v176, s8, v176
	v_sub_u32_e32 v176, v176, v35
	v_lshlrev_b32_e32 v176, 1, v176
	v_mov_b32_e32 v177, 0
	v_lshl_add_u64 v[250:251], v[38:39], 0, v[176:177]
	global_store_dwordx2 v[250:251], v[194:195], off
	v_bfe_u32 v176, v26, 16, 1
	v_bfe_u32 v177, v27, 16, 1
	v_bfe_u32 v178, v28, 16, 1
	v_bfe_u32 v179, v29, 16, 1
	v_add3_u32 v176, v26, v176, s31
	v_add3_u32 v177, v27, v177, s31
	v_add3_u32 v178, v28, v178, s31
	v_add3_u32 v179, v29, v179, s31
	s_mov_b32 vcc_lo, 0x55555555
	s_mov_b32 vcc_hi, 0x55555555
	v_cndmask_b32_dpp v250, v177, v176, vcc quad_perm:[1,0,3,2] row_mask:0xf bank_mask:0xf
	v_cndmask_b32_dpp v251, v179, v178, vcc quad_perm:[1,0,3,2] row_mask:0xf bank_mask:0xf
	s_not_b64 vcc, vcc
	v_cndmask_b32_dpp v176, v176, v177, vcc quad_perm:[1,0,3,2] row_mask:0xf bank_mask:0xf
	v_cndmask_b32_dpp v178, v178, v179, vcc quad_perm:[1,0,3,2] row_mask:0xf bank_mask:0xf
	s_nop 1
	v_perm_b32 v176, v176, v250, v40
	v_perm_b32 v178, v178, v251, v40
	s_mov_b32 vcc_lo, 0x33333333
	s_mov_b32 vcc_hi, 0x33333333
	v_cndmask_b32_dpp v194, v178, v176, vcc quad_perm:[2,3,0,1] row_mask:0xf bank_mask:0xf
	s_not_b64 vcc, vcc
	v_cndmask_b32_dpp v195, v176, v178, vcc quad_perm:[2,3,0,1] row_mask:0xf bank_mask:0xf
	v_or_b32_e32 v176, 16, v37
	v_mul_u32_u24_e32 v176, s8, v176
	v_sub_u32_e32 v176, v176, v35
	v_lshlrev_b32_e32 v176, 1, v176
	v_mov_b32_e32 v177, 0
	v_lshl_add_u64 v[250:251], v[38:39], 0, v[176:177]
	global_store_dwordx2 v[250:251], v[194:195], off
	v_bfe_u32 v176, v22, 16, 1
	v_bfe_u32 v177, v23, 16, 1
	v_bfe_u32 v178, v24, 16, 1
	v_bfe_u32 v179, v25, 16, 1
	v_add3_u32 v176, v22, v176, s31
	v_add3_u32 v177, v23, v177, s31
	v_add3_u32 v178, v24, v178, s31
	v_add3_u32 v179, v25, v179, s31
	s_mov_b32 vcc_lo, 0x55555555
	s_mov_b32 vcc_hi, 0x55555555
	v_cndmask_b32_dpp v250, v177, v176, vcc quad_perm:[1,0,3,2] row_mask:0xf bank_mask:0xf
	v_cndmask_b32_dpp v251, v179, v178, vcc quad_perm:[1,0,3,2] row_mask:0xf bank_mask:0xf
	s_not_b64 vcc, vcc
	v_cndmask_b32_dpp v176, v176, v177, vcc quad_perm:[1,0,3,2] row_mask:0xf bank_mask:0xf
	v_cndmask_b32_dpp v178, v178, v179, vcc quad_perm:[1,0,3,2] row_mask:0xf bank_mask:0xf
	s_nop 1
	v_perm_b32 v176, v176, v250, v40
	v_perm_b32 v178, v178, v251, v40
	s_mov_b32 vcc_lo, 0x33333333
	s_mov_b32 vcc_hi, 0x33333333
	v_cndmask_b32_dpp v194, v178, v176, vcc quad_perm:[2,3,0,1] row_mask:0xf bank_mask:0xf
	s_not_b64 vcc, vcc
	v_cndmask_b32_dpp v195, v176, v178, vcc quad_perm:[2,3,0,1] row_mask:0xf bank_mask:0xf
	v_or_b32_e32 v176, 32, v37
	v_mul_u32_u24_e32 v176, s8, v176
	v_sub_u32_e32 v176, v176, v35
	v_lshlrev_b32_e32 v176, 1, v176
	v_mov_b32_e32 v177, 0
	v_lshl_add_u64 v[250:251], v[38:39], 0, v[176:177]
	global_store_dwordx2 v[250:251], v[194:195], off
	v_bfe_u32 v176, v18, 16, 1
	v_bfe_u32 v177, v19, 16, 1
	v_bfe_u32 v178, v20, 16, 1
	v_bfe_u32 v179, v21, 16, 1
	v_add3_u32 v176, v18, v176, s31
	v_add3_u32 v177, v19, v177, s31
	v_add3_u32 v178, v20, v178, s31
	v_add3_u32 v179, v21, v179, s31
	s_mov_b32 vcc_lo, 0x55555555
	s_mov_b32 vcc_hi, 0x55555555
	v_cndmask_b32_dpp v250, v177, v176, vcc quad_perm:[1,0,3,2] row_mask:0xf bank_mask:0xf
	v_cndmask_b32_dpp v251, v179, v178, vcc quad_perm:[1,0,3,2] row_mask:0xf bank_mask:0xf
	s_not_b64 vcc, vcc
	v_cndmask_b32_dpp v176, v176, v177, vcc quad_perm:[1,0,3,2] row_mask:0xf bank_mask:0xf
	v_cndmask_b32_dpp v178, v178, v179, vcc quad_perm:[1,0,3,2] row_mask:0xf bank_mask:0xf
	s_nop 1
	v_perm_b32 v176, v176, v250, v40
	v_perm_b32 v178, v178, v251, v40
	s_mov_b32 vcc_lo, 0x33333333
	s_mov_b32 vcc_hi, 0x33333333
	v_cndmask_b32_dpp v194, v178, v176, vcc quad_perm:[2,3,0,1] row_mask:0xf bank_mask:0xf
	s_not_b64 vcc, vcc
	v_cndmask_b32_dpp v195, v176, v178, vcc quad_perm:[2,3,0,1] row_mask:0xf bank_mask:0xf
	v_or_b32_e32 v176, 48, v37
	v_mul_u32_u24_e32 v176, s8, v176
	v_sub_u32_e32 v176, v176, v35
	v_lshlrev_b32_e32 v176, 1, v176
	v_mov_b32_e32 v177, 0
	v_lshl_add_u64 v[250:251], v[38:39], 0, v[176:177]
	global_store_dwordx2 v[250:251], v[194:195], off
	s_mov_b64 s[0:1], 0

.LBB0_1618:
	v_lshlrev_b32_e32 v34, 1, v34
	v_mov_b32_e32 v35, v1
	v_lshl_add_u64 v[34:35], v[38:39], 0, v[34:35]
	v_and_b32_e32 v36, 3, v166
	v_add_u32_e32 v37, v148, v36
	v_mov_b32_e32 v38, 0x7060302
	v_bfe_u32 v176, v30, 16, 1
	v_bfe_u32 v177, v31, 16, 1
	v_bfe_u32 v178, v32, 16, 1
	v_bfe_u32 v179, v33, 16, 1
	v_add3_u32 v176, v30, v176, s31
	v_add3_u32 v177, v31, v177, s31
	v_add3_u32 v178, v32, v178, s31
	v_add3_u32 v179, v33, v179, s31
	s_mov_b32 vcc_lo, 0x55555555
	s_mov_b32 vcc_hi, 0x55555555
	v_cndmask_b32_dpp v250, v177, v176, vcc quad_perm:[1,0,3,2] row_mask:0xf bank_mask:0xf
	v_cndmask_b32_dpp v251, v179, v178, vcc quad_perm:[1,0,3,2] row_mask:0xf bank_mask:0xf
	s_not_b64 vcc, vcc
	v_cndmask_b32_dpp v176, v176, v177, vcc quad_perm:[1,0,3,2] row_mask:0xf bank_mask:0xf
	v_cndmask_b32_dpp v178, v178, v179, vcc quad_perm:[1,0,3,2] row_mask:0xf bank_mask:0xf
	s_nop 1
	v_perm_b32 v176, v176, v250, v38
	v_perm_b32 v178, v178, v251, v38
	s_mov_b32 vcc_lo, 0x33333333
	s_mov_b32 vcc_hi, 0x33333333
	v_cndmask_b32_dpp v194, v178, v176, vcc quad_perm:[2,3,0,1] row_mask:0xf bank_mask:0xf
	s_not_b64 vcc, vcc
	v_cndmask_b32_dpp v195, v176, v178, vcc quad_perm:[2,3,0,1] row_mask:0xf bank_mask:0xf
	v_mov_b32_e32 v176, v37
	v_mul_u32_u24_e32 v176, s8, v176
	v_sub_u32_e32 v176, v176, v36
	v_lshlrev_b32_e32 v176, 1, v176
	v_mov_b32_e32 v177, 0
	v_lshl_add_u64 v[250:251], v[34:35], 0, v[176:177]
	global_store_dwordx2 v[250:251], v[194:195], off
	v_bfe_u32 v176, v26, 16, 1
	v_bfe_u32 v177, v27, 16, 1
	v_bfe_u32 v178, v28, 16, 1
	v_bfe_u32 v179, v29, 16, 1
	v_add3_u32 v176, v26, v176, s31
	v_add3_u32 v177, v27, v177, s31
	v_add3_u32 v178, v28, v178, s31
	v_add3_u32 v179, v29, v179, s31
	s_mov_b32 vcc_lo, 0x55555555
	s_mov_b32 vcc_hi, 0x55555555
	v_cndmask_b32_dpp v250, v177, v176, vcc quad_perm:[1,0,3,2] row_mask:0xf bank_mask:0xf
	v_cndmask_b32_dpp v251, v179, v178, vcc quad_perm:[1,0,3,2] row_mask:0xf bank_mask:0xf
	s_not_b64 vcc, vcc
	v_cndmask_b32_dpp v176, v176, v177, vcc quad_perm:[1,0,3,2] row_mask:0xf bank_mask:0xf
	v_cndmask_b32_dpp v178, v178, v179, vcc quad_perm:[1,0,3,2] row_mask:0xf bank_mask:0xf
	s_nop 1
	v_perm_b32 v176, v176, v250, v38
	v_perm_b32 v178, v178, v251, v38
	s_mov_b32 vcc_lo, 0x33333333
	s_mov_b32 vcc_hi, 0x33333333
	v_cndmask_b32_dpp v194, v178, v176, vcc quad_perm:[2,3,0,1] row_mask:0xf bank_mask:0xf
	s_not_b64 vcc, vcc
	v_cndmask_b32_dpp v195, v176, v178, vcc quad_perm:[2,3,0,1] row_mask:0xf bank_mask:0xf
	v_or_b32_e32 v176, 16, v37
	v_mul_u32_u24_e32 v176, s8, v176
	v_sub_u32_e32 v176, v176, v36
	v_lshlrev_b32_e32 v176, 1, v176
	v_mov_b32_e32 v177, 0
	v_lshl_add_u64 v[250:251], v[34:35], 0, v[176:177]
	global_store_dwordx2 v[250:251], v[194:195], off
	v_bfe_u32 v176, v22, 16, 1
	v_bfe_u32 v177, v23, 16, 1
	v_bfe_u32 v178, v24, 16, 1
	v_bfe_u32 v179, v25, 16, 1
	v_add3_u32 v176, v22, v176, s31
	v_add3_u32 v177, v23, v177, s31
	v_add3_u32 v178, v24, v178, s31
	v_add3_u32 v179, v25, v179, s31
	s_mov_b32 vcc_lo, 0x55555555
	s_mov_b32 vcc_hi, 0x55555555
	v_cndmask_b32_dpp v250, v177, v176, vcc quad_perm:[1,0,3,2] row_mask:0xf bank_mask:0xf
	v_cndmask_b32_dpp v251, v179, v178, vcc quad_perm:[1,0,3,2] row_mask:0xf bank_mask:0xf
	s_not_b64 vcc, vcc
	v_cndmask_b32_dpp v176, v176, v177, vcc quad_perm:[1,0,3,2] row_mask:0xf bank_mask:0xf
	v_cndmask_b32_dpp v178, v178, v179, vcc quad_perm:[1,0,3,2] row_mask:0xf bank_mask:0xf
	s_nop 1
	v_perm_b32 v176, v176, v250, v38
	v_perm_b32 v178, v178, v251, v38
	s_mov_b32 vcc_lo, 0x33333333
	s_mov_b32 vcc_hi, 0x33333333
	v_cndmask_b32_dpp v194, v178, v176, vcc quad_perm:[2,3,0,1] row_mask:0xf bank_mask:0xf
	s_not_b64 vcc, vcc
	v_cndmask_b32_dpp v195, v176, v178, vcc quad_perm:[2,3,0,1] row_mask:0xf bank_mask:0xf
	v_or_b32_e32 v176, 32, v37
	v_mul_u32_u24_e32 v176, s8, v176
	v_sub_u32_e32 v176, v176, v36
	v_lshlrev_b32_e32 v176, 1, v176
	v_mov_b32_e32 v177, 0
	v_lshl_add_u64 v[250:251], v[34:35], 0, v[176:177]
	global_store_dwordx2 v[250:251], v[194:195], off
	v_bfe_u32 v176, v18, 16, 1
	v_bfe_u32 v177, v19, 16, 1
	v_bfe_u32 v178, v20, 16, 1
	v_bfe_u32 v179, v21, 16, 1
	v_add3_u32 v176, v18, v176, s31
	v_add3_u32 v177, v19, v177, s31
	v_add3_u32 v178, v20, v178, s31
	v_add3_u32 v179, v21, v179, s31
	s_mov_b32 vcc_lo, 0x55555555
	s_mov_b32 vcc_hi, 0x55555555
	v_cndmask_b32_dpp v250, v177, v176, vcc quad_perm:[1,0,3,2] row_mask:0xf bank_mask:0xf
	v_cndmask_b32_dpp v251, v179, v178, vcc quad_perm:[1,0,3,2] row_mask:0xf bank_mask:0xf
	s_not_b64 vcc, vcc
	v_cndmask_b32_dpp v176, v176, v177, vcc quad_perm:[1,0,3,2] row_mask:0xf bank_mask:0xf
	v_cndmask_b32_dpp v178, v178, v179, vcc quad_perm:[1,0,3,2] row_mask:0xf bank_mask:0xf
	s_nop 1
	v_perm_b32 v176, v176, v250, v38
	v_perm_b32 v178, v178, v251, v38
	s_mov_b32 vcc_lo, 0x33333333
	s_mov_b32 vcc_hi, 0x33333333
	v_cndmask_b32_dpp v194, v178, v176, vcc quad_perm:[2,3,0,1] row_mask:0xf bank_mask:0xf
	s_not_b64 vcc, vcc
	v_cndmask_b32_dpp v195, v176, v178, vcc quad_perm:[2,3,0,1] row_mask:0xf bank_mask:0xf
	v_or_b32_e32 v176, 48, v37
	v_mul_u32_u24_e32 v176, s8, v176
	v_sub_u32_e32 v176, v176, v36
	v_lshlrev_b32_e32 v176, 1, v176
	v_mov_b32_e32 v177, 0
	v_lshl_add_u64 v[250:251], v[34:35], 0, v[176:177]
	global_store_dwordx2 v[250:251], v[194:195], off

.LBB0_1644:
	v_lshlrev_b32_e32 v22, 1, v18
	v_mov_b32_e32 v23, v1
	v_lshl_add_u64 v[22:23], v[24:25], 0, v[22:23]
	v_and_b32_e32 v19, 3, v166
	v_add_u32_e32 v21, v148, v19
	v_mov_b32_e32 v24, 0x7060302
	v_bfe_u32 v176, v14, 16, 1
	v_bfe_u32 v177, v15, 16, 1
	v_bfe_u32 v178, v16, 16, 1
	v_bfe_u32 v179, v17, 16, 1
	v_add3_u32 v176, v14, v176, s31
	v_add3_u32 v177, v15, v177, s31
	v_add3_u32 v178, v16, v178, s31
	v_add3_u32 v179, v17, v179, s31
	s_mov_b32 vcc_lo, 0x55555555
	s_mov_b32 vcc_hi, 0x55555555
	v_cndmask_b32_dpp v250, v177, v176, vcc quad_perm:[1,0,3,2] row_mask:0xf bank_mask:0xf
	v_cndmask_b32_dpp v251, v179, v178, vcc quad_perm:[1,0,3,2] row_mask:0xf bank_mask:0xf
	s_not_b64 vcc, vcc
	v_cndmask_b32_dpp v176, v176, v177, vcc quad_perm:[1,0,3,2] row_mask:0xf bank_mask:0xf
	v_cndmask_b32_dpp v178, v178, v179, vcc quad_perm:[1,0,3,2] row_mask:0xf bank_mask:0xf
	s_nop 1
	v_perm_b32 v176, v176, v250, v24
	v_perm_b32 v178, v178, v251, v24
	s_mov_b32 vcc_lo, 0x33333333
	s_mov_b32 vcc_hi, 0x33333333
	v_cndmask_b32_dpp v194, v178, v176, vcc quad_perm:[2,3,0,1] row_mask:0xf bank_mask:0xf
	s_not_b64 vcc, vcc
	v_cndmask_b32_dpp v195, v176, v178, vcc quad_perm:[2,3,0,1] row_mask:0xf bank_mask:0xf
	v_mov_b32_e32 v176, v21
	v_mul_u32_u24_e32 v176, s6, v176
	v_sub_u32_e32 v176, v176, v19
	v_lshlrev_b32_e32 v176, 1, v176
	v_mov_b32_e32 v177, 0
	v_lshl_add_u64 v[250:251], v[22:23], 0, v[176:177]
	global_store_dwordx2 v[250:251], v[194:195], off
	v_bfe_u32 v176, v10, 16, 1
	v_bfe_u32 v177, v11, 16, 1
	v_bfe_u32 v178, v12, 16, 1
	v_bfe_u32 v179, v13, 16, 1
	v_add3_u32 v176, v10, v176, s31
	v_add3_u32 v177, v11, v177, s31
	v_add3_u32 v178, v12, v178, s31
	v_add3_u32 v179, v13, v179, s31
	s_mov_b32 vcc_lo, 0x55555555
	s_mov_b32 vcc_hi, 0x55555555
	v_cndmask_b32_dpp v250, v177, v176, vcc quad_perm:[1,0,3,2] row_mask:0xf bank_mask:0xf
	v_cndmask_b32_dpp v251, v179, v178, vcc quad_perm:[1,0,3,2] row_mask:0xf bank_mask:0xf
	s_not_b64 vcc, vcc
	v_cndmask_b32_dpp v176, v176, v177, vcc quad_perm:[1,0,3,2] row_mask:0xf bank_mask:0xf
	v_cndmask_b32_dpp v178, v178, v179, vcc quad_perm:[1,0,3,2] row_mask:0xf bank_mask:0xf
	s_nop 1
	v_perm_b32 v176, v176, v250, v24
	v_perm_b32 v178, v178, v251, v24
	s_mov_b32 vcc_lo, 0x33333333
	s_mov_b32 vcc_hi, 0x33333333
	v_cndmask_b32_dpp v194, v178, v176, vcc quad_perm:[2,3,0,1] row_mask:0xf bank_mask:0xf
	s_not_b64 vcc, vcc
	v_cndmask_b32_dpp v195, v176, v178, vcc quad_perm:[2,3,0,1] row_mask:0xf bank_mask:0xf
	v_or_b32_e32 v176, 16, v21
	v_mul_u32_u24_e32 v176, s6, v176
	v_sub_u32_e32 v176, v176, v19
	v_lshlrev_b32_e32 v176, 1, v176
	v_mov_b32_e32 v177, 0
	v_lshl_add_u64 v[250:251], v[22:23], 0, v[176:177]
	global_store_dwordx2 v[250:251], v[194:195], off
	v_bfe_u32 v176, v6, 16, 1
	v_bfe_u32 v177, v7, 16, 1
	v_bfe_u32 v178, v8, 16, 1
	v_bfe_u32 v179, v9, 16, 1
	v_add3_u32 v176, v6, v176, s31
	v_add3_u32 v177, v7, v177, s31
	v_add3_u32 v178, v8, v178, s31
	v_add3_u32 v179, v9, v179, s31
	s_mov_b32 vcc_lo, 0x55555555
	s_mov_b32 vcc_hi, 0x55555555
	v_cndmask_b32_dpp v250, v177, v176, vcc quad_perm:[1,0,3,2] row_mask:0xf bank_mask:0xf
	v_cndmask_b32_dpp v251, v179, v178, vcc quad_perm:[1,0,3,2] row_mask:0xf bank_mask:0xf
	s_not_b64 vcc, vcc
	v_cndmask_b32_dpp v176, v176, v177, vcc quad_perm:[1,0,3,2] row_mask:0xf bank_mask:0xf
	v_cndmask_b32_dpp v178, v178, v179, vcc quad_perm:[1,0,3,2] row_mask:0xf bank_mask:0xf
	s_nop 1
	v_perm_b32 v176, v176, v250, v24
	v_perm_b32 v178, v178, v251, v24
	s_mov_b32 vcc_lo, 0x33333333
	s_mov_b32 vcc_hi, 0x33333333
	v_cndmask_b32_dpp v194, v178, v176, vcc quad_perm:[2,3,0,1] row_mask:0xf bank_mask:0xf
	s_not_b64 vcc, vcc
	v_cndmask_b32_dpp v195, v176, v178, vcc quad_perm:[2,3,0,1] row_mask:0xf bank_mask:0xf
	v_or_b32_e32 v176, 32, v21
	v_mul_u32_u24_e32 v176, s6, v176
	v_sub_u32_e32 v176, v176, v19
	v_lshlrev_b32_e32 v176, 1, v176
	v_mov_b32_e32 v177, 0
	v_lshl_add_u64 v[250:251], v[22:23], 0, v[176:177]
	global_store_dwordx2 v[250:251], v[194:195], off
	v_bfe_u32 v176, v2, 16, 1
	v_bfe_u32 v177, v3, 16, 1
	v_bfe_u32 v178, v4, 16, 1
	v_bfe_u32 v179, v5, 16, 1
	v_add3_u32 v176, v2, v176, s31
	v_add3_u32 v177, v3, v177, s31
	v_add3_u32 v178, v4, v178, s31
	v_add3_u32 v179, v5, v179, s31
	s_mov_b32 vcc_lo, 0x55555555
	s_mov_b32 vcc_hi, 0x55555555
	v_cndmask_b32_dpp v250, v177, v176, vcc quad_perm:[1,0,3,2] row_mask:0xf bank_mask:0xf
	v_cndmask_b32_dpp v251, v179, v178, vcc quad_perm:[1,0,3,2] row_mask:0xf bank_mask:0xf
	s_not_b64 vcc, vcc
	v_cndmask_b32_dpp v176, v176, v177, vcc quad_perm:[1,0,3,2] row_mask:0xf bank_mask:0xf
	v_cndmask_b32_dpp v178, v178, v179, vcc quad_perm:[1,0,3,2] row_mask:0xf bank_mask:0xf
	s_nop 1
	v_perm_b32 v176, v176, v250, v24
	v_perm_b32 v178, v178, v251, v24
	s_mov_b32 vcc_lo, 0x33333333
	s_mov_b32 vcc_hi, 0x33333333
	v_cndmask_b32_dpp v194, v178, v176, vcc quad_perm:[2,3,0,1] row_mask:0xf bank_mask:0xf
	s_not_b64 vcc, vcc
	v_cndmask_b32_dpp v195, v176, v178, vcc quad_perm:[2,3,0,1] row_mask:0xf bank_mask:0xf
	v_or_b32_e32 v176, 48, v21
	v_mul_u32_u24_e32 v176, s6, v176
	v_sub_u32_e32 v176, v176, v19
	v_lshlrev_b32_e32 v176, 1, v176
	v_mov_b32_e32 v177, 0
	v_lshl_add_u64 v[250:251], v[22:23], 0, v[176:177]
	global_store_dwordx2 v[250:251], v[194:195], off
	s_mov_b64 s[0:1], 0

.LBB0_1665:
	v_lshlrev_b32_e32 v0, 1, v18
	v_mov_b32_e32 v1, v1
	v_lshl_add_u64 v[18:19], v[22:23], 0, v[0:1]
	v_and_b32_e32 v0, 3, v166
	v_add_u32_e32 v20, v148, v0
	v_mov_b32_e32 v21, 0x7060302
	v_bfe_u32 v176, v14, 16, 1
	v_bfe_u32 v177, v15, 16, 1
	v_bfe_u32 v178, v16, 16, 1
	v_bfe_u32 v179, v17, 16, 1
	v_add3_u32 v176, v14, v176, s31
	v_add3_u32 v177, v15, v177, s31
	v_add3_u32 v178, v16, v178, s31
	v_add3_u32 v179, v17, v179, s31
	s_mov_b32 vcc_lo, 0x55555555
	s_mov_b32 vcc_hi, 0x55555555
	v_cndmask_b32_dpp v250, v177, v176, vcc quad_perm:[1,0,3,2] row_mask:0xf bank_mask:0xf
	v_cndmask_b32_dpp v251, v179, v178, vcc quad_perm:[1,0,3,2] row_mask:0xf bank_mask:0xf
	s_not_b64 vcc, vcc
	v_cndmask_b32_dpp v176, v176, v177, vcc quad_perm:[1,0,3,2] row_mask:0xf bank_mask:0xf
	v_cndmask_b32_dpp v178, v178, v179, vcc quad_perm:[1,0,3,2] row_mask:0xf bank_mask:0xf
	s_nop 1
	v_perm_b32 v176, v176, v250, v21
	v_perm_b32 v178, v178, v251, v21
	s_mov_b32 vcc_lo, 0x33333333
	s_mov_b32 vcc_hi, 0x33333333
	v_cndmask_b32_dpp v194, v178, v176, vcc quad_perm:[2,3,0,1] row_mask:0xf bank_mask:0xf
	s_not_b64 vcc, vcc
	v_cndmask_b32_dpp v195, v176, v178, vcc quad_perm:[2,3,0,1] row_mask:0xf bank_mask:0xf
	v_mov_b32_e32 v176, v20
	v_mul_u32_u24_e32 v176, s6, v176
	v_sub_u32_e32 v176, v176, v0
	v_lshlrev_b32_e32 v176, 1, v176
	v_mov_b32_e32 v177, 0
	v_lshl_add_u64 v[250:251], v[18:19], 0, v[176:177]
	global_store_dwordx2 v[250:251], v[194:195], off
	v_bfe_u32 v176, v10, 16, 1
	v_bfe_u32 v177, v11, 16, 1
	v_bfe_u32 v178, v12, 16, 1
	v_bfe_u32 v179, v13, 16, 1
	v_add3_u32 v176, v10, v176, s31
	v_add3_u32 v177, v11, v177, s31
	v_add3_u32 v178, v12, v178, s31
	v_add3_u32 v179, v13, v179, s31
	s_mov_b32 vcc_lo, 0x55555555
	s_mov_b32 vcc_hi, 0x55555555
	v_cndmask_b32_dpp v250, v177, v176, vcc quad_perm:[1,0,3,2] row_mask:0xf bank_mask:0xf
	v_cndmask_b32_dpp v251, v179, v178, vcc quad_perm:[1,0,3,2] row_mask:0xf bank_mask:0xf
	s_not_b64 vcc, vcc
	v_cndmask_b32_dpp v176, v176, v177, vcc quad_perm:[1,0,3,2] row_mask:0xf bank_mask:0xf
	v_cndmask_b32_dpp v178, v178, v179, vcc quad_perm:[1,0,3,2] row_mask:0xf bank_mask:0xf
	s_nop 1
	v_perm_b32 v176, v176, v250, v21
	v_perm_b32 v178, v178, v251, v21
	s_mov_b32 vcc_lo, 0x33333333
	s_mov_b32 vcc_hi, 0x33333333
	v_cndmask_b32_dpp v194, v178, v176, vcc quad_perm:[2,3,0,1] row_mask:0xf bank_mask:0xf
	s_not_b64 vcc, vcc
	v_cndmask_b32_dpp v195, v176, v178, vcc quad_perm:[2,3,0,1] row_mask:0xf bank_mask:0xf
	v_or_b32_e32 v176, 16, v20
	v_mul_u32_u24_e32 v176, s6, v176
	v_sub_u32_e32 v176, v176, v0
	v_lshlrev_b32_e32 v176, 1, v176
	v_mov_b32_e32 v177, 0
	v_lshl_add_u64 v[250:251], v[18:19], 0, v[176:177]
	global_store_dwordx2 v[250:251], v[194:195], off
	v_bfe_u32 v176, v6, 16, 1
	v_bfe_u32 v177, v7, 16, 1
	v_bfe_u32 v178, v8, 16, 1
	v_bfe_u32 v179, v9, 16, 1
	v_add3_u32 v176, v6, v176, s31
	v_add3_u32 v177, v7, v177, s31
	v_add3_u32 v178, v8, v178, s31
	v_add3_u32 v179, v9, v179, s31
	s_mov_b32 vcc_lo, 0x55555555
	s_mov_b32 vcc_hi, 0x55555555
	v_cndmask_b32_dpp v250, v177, v176, vcc quad_perm:[1,0,3,2] row_mask:0xf bank_mask:0xf
	v_cndmask_b32_dpp v251, v179, v178, vcc quad_perm:[1,0,3,2] row_mask:0xf bank_mask:0xf
	s_not_b64 vcc, vcc
	v_cndmask_b32_dpp v176, v176, v177, vcc quad_perm:[1,0,3,2] row_mask:0xf bank_mask:0xf
	v_cndmask_b32_dpp v178, v178, v179, vcc quad_perm:[1,0,3,2] row_mask:0xf bank_mask:0xf
	s_nop 1
	v_perm_b32 v176, v176, v250, v21
	v_perm_b32 v178, v178, v251, v21
	s_mov_b32 vcc_lo, 0x33333333
	s_mov_b32 vcc_hi, 0x33333333
	v_cndmask_b32_dpp v194, v178, v176, vcc quad_perm:[2,3,0,1] row_mask:0xf bank_mask:0xf
	s_not_b64 vcc, vcc
	v_cndmask_b32_dpp v195, v176, v178, vcc quad_perm:[2,3,0,1] row_mask:0xf bank_mask:0xf
	v_or_b32_e32 v176, 32, v20
	v_mul_u32_u24_e32 v176, s6, v176
	v_sub_u32_e32 v176, v176, v0
	v_lshlrev_b32_e32 v176, 1, v176
	v_mov_b32_e32 v177, 0
	v_lshl_add_u64 v[250:251], v[18:19], 0, v[176:177]
	global_store_dwordx2 v[250:251], v[194:195], off
	v_bfe_u32 v176, v2, 16, 1
	v_bfe_u32 v177, v3, 16, 1
	v_bfe_u32 v178, v4, 16, 1
	v_bfe_u32 v179, v5, 16, 1
	v_add3_u32 v176, v2, v176, s31
	v_add3_u32 v177, v3, v177, s31
	v_add3_u32 v178, v4, v178, s31
	v_add3_u32 v179, v5, v179, s31
	s_mov_b32 vcc_lo, 0x55555555
	s_mov_b32 vcc_hi, 0x55555555
	v_cndmask_b32_dpp v250, v177, v176, vcc quad_perm:[1,0,3,2] row_mask:0xf bank_mask:0xf
	v_cndmask_b32_dpp v251, v179, v178, vcc quad_perm:[1,0,3,2] row_mask:0xf bank_mask:0xf
	s_not_b64 vcc, vcc
	v_cndmask_b32_dpp v176, v176, v177, vcc quad_perm:[1,0,3,2] row_mask:0xf bank_mask:0xf
	v_cndmask_b32_dpp v178, v178, v179, vcc quad_perm:[1,0,3,2] row_mask:0xf bank_mask:0xf
	s_nop 1
	v_perm_b32 v176, v176, v250, v21
	v_perm_b32 v178, v178, v251, v21
	s_mov_b32 vcc_lo, 0x33333333
	s_mov_b32 vcc_hi, 0x33333333
	v_cndmask_b32_dpp v194, v178, v176, vcc quad_perm:[2,3,0,1] row_mask:0xf bank_mask:0xf
	s_not_b64 vcc, vcc
	v_cndmask_b32_dpp v195, v176, v178, vcc quad_perm:[2,3,0,1] row_mask:0xf bank_mask:0xf
	v_or_b32_e32 v176, 48, v20
	v_mul_u32_u24_e32 v176, s6, v176
	v_sub_u32_e32 v176, v176, v0
	v_lshlrev_b32_e32 v176, 1, v176
	v_mov_b32_e32 v177, 0
	v_lshl_add_u64 v[250:251], v[18:19], 0, v[176:177]
	global_store_dwordx2 v[250:251], v[194:195], off
